# phases 1 and 10: first K iteration of each tile peeled in front of the loop (C = 0 first-touch MFMAs and the relaxed first-iteration waits live only there); steady loop body has no first-iteration tes
# speedup vs baseline: 1.0138x; 1.0087x over previous
.LBB0_177:
	s_ashr_i32 s45, s44, 31
	v_cmp_lt_i64_e32 vcc, s[46:47], v[144:145]
	s_lshl_b64 s[46:47], s[44:45], 19
	s_add_u32 s46, s68, s46
	s_addc_u32 s47, s69, s47
	s_and_b64 s[48:49], vcc, exec
	s_cselect_b32 s11, s47, s51
	s_cselect_b32 s13, s46, s50
	s_ashr_i32 s43, s42, 31
	s_lshl_b64 s[48:49], s[42:43], 19
	s_add_u32 s48, s26, s48
	s_addc_u32 s49, s27, s49
	s_and_b64 s[54:55], vcc, exec
	s_cselect_b32 s17, s49, s53
	s_cselect_b32 s43, s48, s52
	s_add_u32 s50, s50, 0x40080
	s_addc_u32 s51, s51, 0
	s_add_u32 s45, s52, 0x100
	s_addc_u32 s91, s53, 0
	s_mov_b32 s92, -2
	s_waitcnt lgkmcnt(0)
	ds_read_b128 v[148:151], v159
	ds_read_b128 v[152:155], v159 offset:1024
	ds_read_b128 v[164:167], v159 offset:2048
	ds_read_b128 v[168:171], v159 offset:3072
	s_add_u32 s52, s50, 0xfffc0080
	s_addc_u32 s53, s51, -1
	s_cmp_eq_u32 s92, 12
	s_cselect_b32 s55, s11, s53
	s_cselect_b32 s54, s13, s52
	s_cselect_b32 s53, s17, s91
	s_cselect_b32 s52, s43, s45
	v_lshl_add_u64 v[156:157], s[50:51], 0, v[140:141]
	s_add_i32 m0, s58, 0xc000
	ds_read_b128 v[172:175], v160
	ds_read_b128 v[176:179], v160 offset:1024
	ds_read_b128 v[180:183], v160 offset:2048
	ds_read_b128 v[184:187], v160 offset:3072
	ds_read_b128 v[188:191], v160 offset:4096
	ds_read_b128 v[196:199], v160 offset:5120
	ds_read_b128 v[200:203], v160 offset:6144
	ds_read_b128 v[204:207], v160 offset:7168
	global_load_lds_dwordx4 v[156:157], off
	v_lshl_add_u64 v[156:157], s[50:51], 0, v[142:143]
	s_add_i32 m0, s58, 0xe000
	s_nop 0
	global_load_lds_dwordx4 v[156:157], off
	s_waitcnt lgkmcnt(8)
	s_barrier
	s_waitcnt lgkmcnt(0)
	v_mfma_f32_16x16x32_bf16 v[124:127], v[148:151], v[172:175], 0
	v_mfma_f32_16x16x32_bf16 v[120:123], v[164:167], v[172:175], 0
	v_mfma_f32_16x16x32_bf16 v[108:111], v[148:151], v[180:183], 0
	v_mfma_f32_16x16x32_bf16 v[104:107], v[164:167], v[180:183], 0
	v_mfma_f32_16x16x32_bf16 v[92:95], v[148:151], v[188:191], 0
	v_mfma_f32_16x16x32_bf16 v[88:91], v[164:167], v[188:191], 0
	v_mfma_f32_16x16x32_bf16 v[76:79], v[148:151], v[200:203], 0
	v_mfma_f32_16x16x32_bf16 v[72:75], v[164:167], v[200:203], 0
	v_mfma_f32_16x16x32_bf16 v[124:127], v[152:155], v[176:179], v[124:127]
	v_mfma_f32_16x16x32_bf16 v[120:123], v[168:171], v[176:179], v[120:123]
	v_mfma_f32_16x16x32_bf16 v[108:111], v[152:155], v[184:187], v[108:111]
	v_mfma_f32_16x16x32_bf16 v[104:107], v[168:171], v[184:187], v[104:107]
	v_mfma_f32_16x16x32_bf16 v[92:95], v[152:155], v[196:199], v[92:95]
	v_mfma_f32_16x16x32_bf16 v[88:91], v[168:171], v[196:199], v[88:91]
	v_mfma_f32_16x16x32_bf16 v[76:79], v[152:155], v[204:207], v[76:79]
	v_mfma_f32_16x16x32_bf16 v[72:75], v[168:171], v[204:207], v[72:75]
	s_barrier
	s_add_i32 s93, s89, s57
	v_lshl_add_u64 v[156:157], s[52:53], 0, v[130:131]
	s_mov_b32 m0, s93
	ds_read_b128 v[208:211], v161
	ds_read_b128 v[212:215], v161 offset:1024
	ds_read_b128 v[216:219], v161 offset:2048
	ds_read_b128 v[220:223], v161 offset:3072
	global_load_lds_dwordx4 v[156:157], off
	v_lshl_add_u64 v[224:225], s[52:53], 0, v[134:135]
	s_add_i32 m0, s93, 0x2000
	s_nop 0
	global_load_lds_dwordx4 v[224:225], off
	s_barrier
	s_waitcnt lgkmcnt(0)
	v_mfma_f32_16x16x32_bf16 v[116:119], v[208:211], v[172:175], 0
	v_mfma_f32_16x16x32_bf16 v[112:115], v[216:219], v[172:175], 0
	v_mfma_f32_16x16x32_bf16 v[100:103], v[208:211], v[180:183], 0
	v_mfma_f32_16x16x32_bf16 v[96:99], v[216:219], v[180:183], 0
	v_mfma_f32_16x16x32_bf16 v[84:87], v[208:211], v[188:191], 0
	v_mfma_f32_16x16x32_bf16 v[80:83], v[216:219], v[188:191], 0
	v_mfma_f32_16x16x32_bf16 v[68:71], v[208:211], v[200:203], 0
	v_mfma_f32_16x16x32_bf16 v[64:67], v[216:219], v[200:203], 0
	v_mfma_f32_16x16x32_bf16 v[116:119], v[212:215], v[176:179], v[116:119]
	v_mfma_f32_16x16x32_bf16 v[112:115], v[220:223], v[176:179], v[112:115]
	v_mfma_f32_16x16x32_bf16 v[100:103], v[212:215], v[184:187], v[100:103]
	v_mfma_f32_16x16x32_bf16 v[96:99], v[220:223], v[184:187], v[96:99]
	v_mfma_f32_16x16x32_bf16 v[84:87], v[212:215], v[196:199], v[84:87]
	v_mfma_f32_16x16x32_bf16 v[80:83], v[220:223], v[196:199], v[80:83]
	v_mfma_f32_16x16x32_bf16 v[68:71], v[212:215], v[204:207], v[68:71]
	v_mfma_f32_16x16x32_bf16 v[64:67], v[220:223], v[204:207], v[64:67]
	s_mov_b32 m0, s58
	v_lshl_add_u64 v[226:227], s[54:55], 0, v[128:129]
	s_barrier
	ds_read_b128 v[172:175], v160 offset:16384
	ds_read_b128 v[176:179], v160 offset:17408
	ds_read_b128 v[180:183], v160 offset:18432
	ds_read_b128 v[184:187], v160 offset:19456
	ds_read_b128 v[188:191], v160 offset:20480
	ds_read_b128 v[196:199], v160 offset:21504
	ds_read_b128 v[200:203], v160 offset:22528
	ds_read_b128 v[204:207], v160 offset:23552
	global_load_lds_dwordx4 v[226:227], off
	v_lshl_add_u64 v[228:229], s[54:55], 0, v[132:133]
	s_mov_b32 m0, s59
	s_nop 0
	global_load_lds_dwordx4 v[228:229], off
	s_barrier
	s_waitcnt lgkmcnt(0)
	v_mfma_f32_16x16x32_bf16 v[60:63], v[148:151], v[172:175], 0
	v_mfma_f32_16x16x32_bf16 v[56:59], v[164:167], v[172:175], 0
	v_mfma_f32_16x16x32_bf16 v[44:47], v[148:151], v[180:183], 0
	v_mfma_f32_16x16x32_bf16 v[40:43], v[164:167], v[180:183], 0
	v_mfma_f32_16x16x32_bf16 v[28:31], v[148:151], v[188:191], 0
	v_mfma_f32_16x16x32_bf16 v[24:27], v[164:167], v[188:191], 0
	v_mfma_f32_16x16x32_bf16 v[12:15], v[148:151], v[200:203], 0
	v_mfma_f32_16x16x32_bf16 v[8:11], v[164:167], v[200:203], 0
	v_mfma_f32_16x16x32_bf16 v[60:63], v[152:155], v[176:179], v[60:63]
	v_mfma_f32_16x16x32_bf16 v[56:59], v[168:171], v[176:179], v[56:59]
	v_mfma_f32_16x16x32_bf16 v[44:47], v[152:155], v[184:187], v[44:47]
	v_mfma_f32_16x16x32_bf16 v[40:43], v[168:171], v[184:187], v[40:43]
	v_mfma_f32_16x16x32_bf16 v[28:31], v[152:155], v[196:199], v[28:31]
	v_mfma_f32_16x16x32_bf16 v[24:27], v[168:171], v[196:199], v[24:27]
	v_mfma_f32_16x16x32_bf16 v[12:15], v[152:155], v[204:207], v[12:15]
	v_mfma_f32_16x16x32_bf16 v[8:11], v[168:171], v[204:207], v[8:11]
	s_barrier
	s_add_u32 s94, s52, 0x10000
	s_addc_u32 s95, s53, 0
	s_add_i32 s93, s90, s57
	v_lshl_add_u64 v[148:149], s[94:95], 0, v[130:131]
	s_mov_b32 m0, s93
	s_nop 0
	global_load_lds_dwordx4 v[148:149], off
	v_lshl_add_u64 v[148:149], s[94:95], 0, v[134:135]
	s_add_i32 m0, s93, 0x2000
	s_nop 0
	global_load_lds_dwordx4 v[148:149], off
	s_cmp_eq_u32 s98, 0
	s_cbranch_scc1 .Lk1_w4n
	s_mov_b32 s98, 0
	s_waitcnt vmcnt(24)
	s_branch .Lk1_w4j

.Lk1_w4j:
	s_barrier
	v_mfma_f32_16x16x32_bf16 v[52:55], v[208:211], v[172:175], 0
	v_mfma_f32_16x16x32_bf16 v[48:51], v[216:219], v[172:175], 0
	v_mfma_f32_16x16x32_bf16 v[36:39], v[208:211], v[180:183], 0
	v_mfma_f32_16x16x32_bf16 v[32:35], v[216:219], v[180:183], 0
	v_mfma_f32_16x16x32_bf16 v[20:23], v[208:211], v[188:191], 0
	v_mfma_f32_16x16x32_bf16 v[16:19], v[216:219], v[188:191], 0
	v_mfma_f32_16x16x32_bf16 v[4:7], v[208:211], v[200:203], 0
	v_mfma_f32_16x16x32_bf16 v[0:3], v[216:219], v[200:203], 0
	v_mfma_f32_16x16x32_bf16 v[52:55], v[212:215], v[176:179], v[52:55]
	v_mfma_f32_16x16x32_bf16 v[48:51], v[220:223], v[176:179], v[48:51]
	v_mfma_f32_16x16x32_bf16 v[36:39], v[212:215], v[184:187], v[36:39]
	v_mfma_f32_16x16x32_bf16 v[32:35], v[220:223], v[184:187], v[32:35]
	v_mfma_f32_16x16x32_bf16 v[20:23], v[212:215], v[196:199], v[20:23]
	v_mfma_f32_16x16x32_bf16 v[16:19], v[220:223], v[196:199], v[16:19]
	v_mfma_f32_16x16x32_bf16 v[4:7], v[212:215], v[204:207], v[4:7]
	v_mfma_f32_16x16x32_bf16 v[0:3], v[220:223], v[204:207], v[0:3]
	s_add_i32 s93, 0, 0x18000
	v_add_u32_e32 v136, s93, v158
	s_barrier
	ds_read_b128 v[148:151], v136
	ds_read_b128 v[152:155], v136 offset:1024
	ds_read_b128 v[164:167], v136 offset:2048
	ds_read_b128 v[168:171], v136 offset:3072
	s_add_u32 s54, s54, 0x40000
	s_addc_u32 s55, s55, 0
	s_mov_b32 m0, s60
	v_lshl_add_u64 v[208:209], s[54:55], 0, v[128:129]
	ds_read_b128 v[172:175], v160 offset:32768
	ds_read_b128 v[176:179], v160 offset:33792
	ds_read_b128 v[180:183], v160 offset:34816
	ds_read_b128 v[184:187], v160 offset:35840
	ds_read_b128 v[188:191], v160 offset:36864
	ds_read_b128 v[196:199], v160 offset:37888
	ds_read_b128 v[200:203], v160 offset:38912
	ds_read_b128 v[204:207], v160 offset:39936
	global_load_lds_dwordx4 v[208:209], off
	v_lshl_add_u64 v[208:209], s[54:55], 0, v[132:133]
	s_mov_b32 m0, s61
	s_nop 0
	global_load_lds_dwordx4 v[208:209], off
	s_waitcnt lgkmcnt(8)
	s_barrier
	s_waitcnt lgkmcnt(0)
	v_mfma_f32_16x16x32_bf16 v[124:127], v[148:151], v[172:175], v[124:127]
	v_mfma_f32_16x16x32_bf16 v[120:123], v[164:167], v[172:175], v[120:123]
	v_mfma_f32_16x16x32_bf16 v[108:111], v[148:151], v[180:183], v[108:111]
	v_mfma_f32_16x16x32_bf16 v[104:107], v[164:167], v[180:183], v[104:107]
	v_mfma_f32_16x16x32_bf16 v[92:95], v[148:151], v[188:191], v[92:95]
	v_mfma_f32_16x16x32_bf16 v[88:91], v[164:167], v[188:191], v[88:91]
	v_mfma_f32_16x16x32_bf16 v[76:79], v[148:151], v[200:203], v[76:79]
	v_mfma_f32_16x16x32_bf16 v[72:75], v[164:167], v[200:203], v[72:75]
	v_mfma_f32_16x16x32_bf16 v[124:127], v[152:155], v[176:179], v[124:127]
	v_mfma_f32_16x16x32_bf16 v[120:123], v[168:171], v[176:179], v[120:123]
	v_mfma_f32_16x16x32_bf16 v[108:111], v[152:155], v[184:187], v[108:111]
	v_mfma_f32_16x16x32_bf16 v[104:107], v[168:171], v[184:187], v[104:107]
	v_mfma_f32_16x16x32_bf16 v[92:95], v[152:155], v[196:199], v[92:95]
	v_mfma_f32_16x16x32_bf16 v[88:91], v[168:171], v[196:199], v[88:91]
	v_mfma_f32_16x16x32_bf16 v[76:79], v[152:155], v[204:207], v[76:79]
	v_mfma_f32_16x16x32_bf16 v[72:75], v[168:171], v[204:207], v[72:75]
	s_barrier
	s_add_i32 s54, 0, 0x1c000
	s_add_i32 s55, s93, s57
	v_add_u32_e32 v136, s54, v158
	v_lshl_add_u64 v[156:157], v[156:157], 0, s[0:1]
	s_mov_b32 m0, s55
	ds_read_b128 v[208:211], v136
	ds_read_b128 v[212:215], v136 offset:1024
	ds_read_b128 v[216:219], v136 offset:2048
	ds_read_b128 v[220:223], v136 offset:3072
	global_load_lds_dwordx4 v[156:157], off
	v_lshl_add_u64 v[156:157], v[224:225], 0, s[0:1]
	s_add_i32 m0, s55, 0x2000
	s_nop 0
	global_load_lds_dwordx4 v[156:157], off
	s_barrier
	s_waitcnt lgkmcnt(0)
	v_mfma_f32_16x16x32_bf16 v[116:119], v[208:211], v[172:175], v[116:119]
	v_mfma_f32_16x16x32_bf16 v[112:115], v[216:219], v[172:175], v[112:115]
	v_mfma_f32_16x16x32_bf16 v[100:103], v[208:211], v[180:183], v[100:103]
	v_mfma_f32_16x16x32_bf16 v[96:99], v[216:219], v[180:183], v[96:99]
	v_mfma_f32_16x16x32_bf16 v[84:87], v[208:211], v[188:191], v[84:87]
	v_mfma_f32_16x16x32_bf16 v[80:83], v[216:219], v[188:191], v[80:83]
	v_mfma_f32_16x16x32_bf16 v[68:71], v[208:211], v[200:203], v[68:71]
	v_mfma_f32_16x16x32_bf16 v[64:67], v[216:219], v[200:203], v[64:67]
	v_mfma_f32_16x16x32_bf16 v[116:119], v[212:215], v[176:179], v[116:119]
	v_mfma_f32_16x16x32_bf16 v[112:115], v[220:223], v[176:179], v[112:115]
	v_mfma_f32_16x16x32_bf16 v[100:103], v[212:215], v[184:187], v[100:103]
	v_mfma_f32_16x16x32_bf16 v[96:99], v[220:223], v[184:187], v[96:99]
	v_mfma_f32_16x16x32_bf16 v[84:87], v[212:215], v[196:199], v[84:87]
	v_mfma_f32_16x16x32_bf16 v[80:83], v[220:223], v[196:199], v[80:83]
	v_mfma_f32_16x16x32_bf16 v[68:71], v[212:215], v[204:207], v[68:71]
	v_mfma_f32_16x16x32_bf16 v[64:67], v[220:223], v[204:207], v[64:67]
	s_mov_b32 m0, s65
	v_lshl_add_u64 v[156:157], v[226:227], 0, s[0:1]
	s_waitcnt vmcnt(10)
	s_barrier
	ds_read_b128 v[172:175], v160 offset:49152
	ds_read_b128 v[176:179], v160 offset:50176
	ds_read_b128 v[180:183], v160 offset:51200
	ds_read_b128 v[184:187], v160 offset:52224
	ds_read_b128 v[188:191], v160 offset:53248
	ds_read_b128 v[196:199], v160 offset:54272
	ds_read_b128 v[200:203], v160 offset:55296
	ds_read_b128 v[204:207], v160 offset:56320
	global_load_lds_dwordx4 v[156:157], off
	v_lshl_add_u64 v[156:157], v[228:229], 0, s[0:1]
	s_mov_b32 m0, s66
	s_nop 0
	global_load_lds_dwordx4 v[156:157], off
	s_barrier
	s_waitcnt lgkmcnt(0)
	v_mfma_f32_16x16x32_bf16 v[60:63], v[148:151], v[172:175], v[60:63]
	v_mfma_f32_16x16x32_bf16 v[56:59], v[164:167], v[172:175], v[56:59]
	v_mfma_f32_16x16x32_bf16 v[44:47], v[148:151], v[180:183], v[44:47]
	v_mfma_f32_16x16x32_bf16 v[40:43], v[164:167], v[180:183], v[40:43]
	v_mfma_f32_16x16x32_bf16 v[28:31], v[148:151], v[188:191], v[28:31]
	v_mfma_f32_16x16x32_bf16 v[24:27], v[164:167], v[188:191], v[24:27]
	v_mfma_f32_16x16x32_bf16 v[12:15], v[148:151], v[200:203], v[12:15]
	v_mfma_f32_16x16x32_bf16 v[8:11], v[164:167], v[200:203], v[8:11]
	v_mfma_f32_16x16x32_bf16 v[60:63], v[152:155], v[176:179], v[60:63]
	v_mfma_f32_16x16x32_bf16 v[56:59], v[168:171], v[176:179], v[56:59]
	v_mfma_f32_16x16x32_bf16 v[44:47], v[152:155], v[184:187], v[44:47]
	v_mfma_f32_16x16x32_bf16 v[40:43], v[168:171], v[184:187], v[40:43]
	v_mfma_f32_16x16x32_bf16 v[28:31], v[152:155], v[196:199], v[28:31]
	v_mfma_f32_16x16x32_bf16 v[24:27], v[168:171], v[196:199], v[24:27]
	v_mfma_f32_16x16x32_bf16 v[12:15], v[152:155], v[204:207], v[12:15]
	v_mfma_f32_16x16x32_bf16 v[8:11], v[168:171], v[204:207], v[8:11]
	s_barrier
	s_add_u32 s52, s52, 0x10080
	s_addc_u32 s53, s53, 0
	s_add_i32 s54, s54, s57
	v_lshl_add_u64 v[148:149], s[52:53], 0, v[130:131]
	s_mov_b32 m0, s54
	s_nop 0
	global_load_lds_dwordx4 v[148:149], off
	v_lshl_add_u64 v[148:149], s[52:53], 0, v[134:135]
	s_add_i32 m0, s54, 0x2000
	s_nop 0
	global_load_lds_dwordx4 v[148:149], off
	s_waitcnt vmcnt(6)
	s_barrier
	v_mfma_f32_16x16x32_bf16 v[52:55], v[208:211], v[172:175], v[52:55]
	v_mfma_f32_16x16x32_bf16 v[48:51], v[216:219], v[172:175], v[48:51]
	v_mfma_f32_16x16x32_bf16 v[36:39], v[208:211], v[180:183], v[36:39]
	v_mfma_f32_16x16x32_bf16 v[32:35], v[216:219], v[180:183], v[32:35]
	v_mfma_f32_16x16x32_bf16 v[20:23], v[208:211], v[188:191], v[20:23]
	v_mfma_f32_16x16x32_bf16 v[16:19], v[216:219], v[188:191], v[16:19]
	v_mfma_f32_16x16x32_bf16 v[4:7], v[208:211], v[200:203], v[4:7]
	v_mfma_f32_16x16x32_bf16 v[0:3], v[216:219], v[200:203], v[0:3]
	v_mfma_f32_16x16x32_bf16 v[52:55], v[212:215], v[176:179], v[52:55]
	v_mfma_f32_16x16x32_bf16 v[48:51], v[220:223], v[176:179], v[48:51]
	v_mfma_f32_16x16x32_bf16 v[36:39], v[212:215], v[184:187], v[36:39]
	v_mfma_f32_16x16x32_bf16 v[32:35], v[220:223], v[184:187], v[32:35]
	v_mfma_f32_16x16x32_bf16 v[20:23], v[212:215], v[196:199], v[20:23]
	v_mfma_f32_16x16x32_bf16 v[16:19], v[220:223], v[196:199], v[16:19]
	v_mfma_f32_16x16x32_bf16 v[4:7], v[212:215], v[204:207], v[4:7]
	v_mfma_f32_16x16x32_bf16 v[0:3], v[220:223], v[204:207], v[0:3]
	s_add_i32 s92, s92, 2
	s_add_u32 s50, s50, 0x100
	s_addc_u32 s51, s51, 0
	s_add_u32 s45, s45, 0x100
	s_addc_u32 s91, s91, 0
	s_cmp_gt_u32 s92, 13
	s_barrier
	s_cbranch_scc0 .LBB0_178
.LBB0_178:
	ds_read_b128 v[148:151], v159
	ds_read_b128 v[152:155], v159 offset:1024
	ds_read_b128 v[164:167], v159 offset:2048
	ds_read_b128 v[168:171], v159 offset:3072
	s_add_u32 s52, s50, 0xfffc0080
	s_addc_u32 s53, s51, -1
	s_cmp_eq_u32 s92, 12
	s_cselect_b32 s55, s11, s53
	s_cselect_b32 s54, s13, s52
	s_cselect_b32 s53, s17, s91
	s_cselect_b32 s52, s43, s45
	v_lshl_add_u64 v[156:157], s[50:51], 0, v[140:141]
	s_add_i32 m0, s58, 0xc000
	ds_read_b128 v[172:175], v160
	ds_read_b128 v[176:179], v160 offset:1024
	ds_read_b128 v[180:183], v160 offset:2048
	ds_read_b128 v[184:187], v160 offset:3072
	ds_read_b128 v[188:191], v160 offset:4096
	ds_read_b128 v[196:199], v160 offset:5120
	ds_read_b128 v[200:203], v160 offset:6144
	ds_read_b128 v[204:207], v160 offset:7168
	global_load_lds_dwordx4 v[156:157], off
	v_lshl_add_u64 v[156:157], s[50:51], 0, v[142:143]
	s_add_i32 m0, s58, 0xe000
	s_nop 0
	global_load_lds_dwordx4 v[156:157], off
	s_waitcnt lgkmcnt(8)
	s_barrier
	s_waitcnt lgkmcnt(0)
	v_mfma_f32_16x16x32_bf16 v[124:127], v[148:151], v[172:175], v[124:127]
	v_mfma_f32_16x16x32_bf16 v[120:123], v[164:167], v[172:175], v[120:123]
	v_mfma_f32_16x16x32_bf16 v[108:111], v[148:151], v[180:183], v[108:111]
	v_mfma_f32_16x16x32_bf16 v[104:107], v[164:167], v[180:183], v[104:107]
	v_mfma_f32_16x16x32_bf16 v[92:95], v[148:151], v[188:191], v[92:95]
	v_mfma_f32_16x16x32_bf16 v[88:91], v[164:167], v[188:191], v[88:91]
	v_mfma_f32_16x16x32_bf16 v[76:79], v[148:151], v[200:203], v[76:79]
	v_mfma_f32_16x16x32_bf16 v[72:75], v[164:167], v[200:203], v[72:75]
	v_mfma_f32_16x16x32_bf16 v[124:127], v[152:155], v[176:179], v[124:127]
	v_mfma_f32_16x16x32_bf16 v[120:123], v[168:171], v[176:179], v[120:123]
	v_mfma_f32_16x16x32_bf16 v[108:111], v[152:155], v[184:187], v[108:111]
	v_mfma_f32_16x16x32_bf16 v[104:107], v[168:171], v[184:187], v[104:107]
	v_mfma_f32_16x16x32_bf16 v[92:95], v[152:155], v[196:199], v[92:95]
	v_mfma_f32_16x16x32_bf16 v[88:91], v[168:171], v[196:199], v[88:91]
	v_mfma_f32_16x16x32_bf16 v[76:79], v[152:155], v[204:207], v[76:79]
	v_mfma_f32_16x16x32_bf16 v[72:75], v[168:171], v[204:207], v[72:75]
	s_barrier
	s_add_i32 s93, s89, s57
	v_lshl_add_u64 v[156:157], s[52:53], 0, v[130:131]
	s_mov_b32 m0, s93
	ds_read_b128 v[208:211], v161
	ds_read_b128 v[212:215], v161 offset:1024
	ds_read_b128 v[216:219], v161 offset:2048
	ds_read_b128 v[220:223], v161 offset:3072
	global_load_lds_dwordx4 v[156:157], off
	v_lshl_add_u64 v[224:225], s[52:53], 0, v[134:135]
	s_add_i32 m0, s93, 0x2000
	s_nop 0
	global_load_lds_dwordx4 v[224:225], off
	s_barrier
	s_waitcnt lgkmcnt(0)
	v_mfma_f32_16x16x32_bf16 v[116:119], v[208:211], v[172:175], v[116:119]
	v_mfma_f32_16x16x32_bf16 v[112:115], v[216:219], v[172:175], v[112:115]
	v_mfma_f32_16x16x32_bf16 v[100:103], v[208:211], v[180:183], v[100:103]
	v_mfma_f32_16x16x32_bf16 v[96:99], v[216:219], v[180:183], v[96:99]
	v_mfma_f32_16x16x32_bf16 v[84:87], v[208:211], v[188:191], v[84:87]
	v_mfma_f32_16x16x32_bf16 v[80:83], v[216:219], v[188:191], v[80:83]
	v_mfma_f32_16x16x32_bf16 v[68:71], v[208:211], v[200:203], v[68:71]
	v_mfma_f32_16x16x32_bf16 v[64:67], v[216:219], v[200:203], v[64:67]
	v_mfma_f32_16x16x32_bf16 v[116:119], v[212:215], v[176:179], v[116:119]
	v_mfma_f32_16x16x32_bf16 v[112:115], v[220:223], v[176:179], v[112:115]
	v_mfma_f32_16x16x32_bf16 v[100:103], v[212:215], v[184:187], v[100:103]
	v_mfma_f32_16x16x32_bf16 v[96:99], v[220:223], v[184:187], v[96:99]
	v_mfma_f32_16x16x32_bf16 v[84:87], v[212:215], v[196:199], v[84:87]
	v_mfma_f32_16x16x32_bf16 v[80:83], v[220:223], v[196:199], v[80:83]
	v_mfma_f32_16x16x32_bf16 v[68:71], v[212:215], v[204:207], v[68:71]
	v_mfma_f32_16x16x32_bf16 v[64:67], v[220:223], v[204:207], v[64:67]
	s_mov_b32 m0, s58
	v_lshl_add_u64 v[226:227], s[54:55], 0, v[128:129]
	s_barrier
	ds_read_b128 v[172:175], v160 offset:16384
	ds_read_b128 v[176:179], v160 offset:17408
	ds_read_b128 v[180:183], v160 offset:18432
	ds_read_b128 v[184:187], v160 offset:19456
	ds_read_b128 v[188:191], v160 offset:20480
	ds_read_b128 v[196:199], v160 offset:21504
	ds_read_b128 v[200:203], v160 offset:22528
	ds_read_b128 v[204:207], v160 offset:23552
	global_load_lds_dwordx4 v[226:227], off
	v_lshl_add_u64 v[228:229], s[54:55], 0, v[132:133]
	s_mov_b32 m0, s59
	s_nop 0
	global_load_lds_dwordx4 v[228:229], off
	s_barrier
	s_waitcnt lgkmcnt(0)
	v_mfma_f32_16x16x32_bf16 v[60:63], v[148:151], v[172:175], v[60:63]
	v_mfma_f32_16x16x32_bf16 v[56:59], v[164:167], v[172:175], v[56:59]
	v_mfma_f32_16x16x32_bf16 v[44:47], v[148:151], v[180:183], v[44:47]
	v_mfma_f32_16x16x32_bf16 v[40:43], v[164:167], v[180:183], v[40:43]
	v_mfma_f32_16x16x32_bf16 v[28:31], v[148:151], v[188:191], v[28:31]
	v_mfma_f32_16x16x32_bf16 v[24:27], v[164:167], v[188:191], v[24:27]
	v_mfma_f32_16x16x32_bf16 v[12:15], v[148:151], v[200:203], v[12:15]
	v_mfma_f32_16x16x32_bf16 v[8:11], v[164:167], v[200:203], v[8:11]
	v_mfma_f32_16x16x32_bf16 v[60:63], v[152:155], v[176:179], v[60:63]
	v_mfma_f32_16x16x32_bf16 v[56:59], v[168:171], v[176:179], v[56:59]
	v_mfma_f32_16x16x32_bf16 v[44:47], v[152:155], v[184:187], v[44:47]
	v_mfma_f32_16x16x32_bf16 v[40:43], v[168:171], v[184:187], v[40:43]
	v_mfma_f32_16x16x32_bf16 v[28:31], v[152:155], v[196:199], v[28:31]
	v_mfma_f32_16x16x32_bf16 v[24:27], v[168:171], v[196:199], v[24:27]
	v_mfma_f32_16x16x32_bf16 v[12:15], v[152:155], v[204:207], v[12:15]
	v_mfma_f32_16x16x32_bf16 v[8:11], v[168:171], v[204:207], v[8:11]
	s_barrier
	s_add_u32 s94, s52, 0x10000
	s_addc_u32 s95, s53, 0
	s_add_i32 s93, s90, s57
	v_lshl_add_u64 v[148:149], s[94:95], 0, v[130:131]
	s_mov_b32 m0, s93
	s_nop 0
	global_load_lds_dwordx4 v[148:149], off
	v_lshl_add_u64 v[148:149], s[94:95], 0, v[134:135]
	s_add_i32 m0, s93, 0x2000
	s_nop 0
	global_load_lds_dwordx4 v[148:149], off
	s_waitcnt vmcnt(6)
	s_barrier
	v_mfma_f32_16x16x32_bf16 v[52:55], v[208:211], v[172:175], v[52:55]
	v_mfma_f32_16x16x32_bf16 v[48:51], v[216:219], v[172:175], v[48:51]
	v_mfma_f32_16x16x32_bf16 v[36:39], v[208:211], v[180:183], v[36:39]
	v_mfma_f32_16x16x32_bf16 v[32:35], v[216:219], v[180:183], v[32:35]
	v_mfma_f32_16x16x32_bf16 v[20:23], v[208:211], v[188:191], v[20:23]
	v_mfma_f32_16x16x32_bf16 v[16:19], v[216:219], v[188:191], v[16:19]
	v_mfma_f32_16x16x32_bf16 v[4:7], v[208:211], v[200:203], v[4:7]
	v_mfma_f32_16x16x32_bf16 v[0:3], v[216:219], v[200:203], v[0:3]
	v_mfma_f32_16x16x32_bf16 v[52:55], v[212:215], v[176:179], v[52:55]
	v_mfma_f32_16x16x32_bf16 v[48:51], v[220:223], v[176:179], v[48:51]
	v_mfma_f32_16x16x32_bf16 v[36:39], v[212:215], v[184:187], v[36:39]
	v_mfma_f32_16x16x32_bf16 v[32:35], v[220:223], v[184:187], v[32:35]
	v_mfma_f32_16x16x32_bf16 v[20:23], v[212:215], v[196:199], v[20:23]
	v_mfma_f32_16x16x32_bf16 v[16:19], v[220:223], v[196:199], v[16:19]
	v_mfma_f32_16x16x32_bf16 v[4:7], v[212:215], v[204:207], v[4:7]
	v_mfma_f32_16x16x32_bf16 v[0:3], v[220:223], v[204:207], v[0:3]
	s_add_i32 s93, 0, 0x18000
	v_add_u32_e32 v136, s93, v158
	s_barrier
	ds_read_b128 v[148:151], v136
	ds_read_b128 v[152:155], v136 offset:1024
	ds_read_b128 v[164:167], v136 offset:2048
	ds_read_b128 v[168:171], v136 offset:3072
	s_add_u32 s54, s54, 0x40000
	s_addc_u32 s55, s55, 0
	s_mov_b32 m0, s60
	v_lshl_add_u64 v[208:209], s[54:55], 0, v[128:129]
	ds_read_b128 v[172:175], v160 offset:32768
	ds_read_b128 v[176:179], v160 offset:33792
	ds_read_b128 v[180:183], v160 offset:34816
	ds_read_b128 v[184:187], v160 offset:35840
	ds_read_b128 v[188:191], v160 offset:36864
	ds_read_b128 v[196:199], v160 offset:37888
	ds_read_b128 v[200:203], v160 offset:38912
	ds_read_b128 v[204:207], v160 offset:39936
	global_load_lds_dwordx4 v[208:209], off
	v_lshl_add_u64 v[208:209], s[54:55], 0, v[132:133]
	s_mov_b32 m0, s61
	s_nop 0
	global_load_lds_dwordx4 v[208:209], off
	s_waitcnt lgkmcnt(8)
	s_barrier
	s_waitcnt lgkmcnt(0)
	v_mfma_f32_16x16x32_bf16 v[124:127], v[148:151], v[172:175], v[124:127]
	v_mfma_f32_16x16x32_bf16 v[120:123], v[164:167], v[172:175], v[120:123]
	v_mfma_f32_16x16x32_bf16 v[108:111], v[148:151], v[180:183], v[108:111]
	v_mfma_f32_16x16x32_bf16 v[104:107], v[164:167], v[180:183], v[104:107]
	v_mfma_f32_16x16x32_bf16 v[92:95], v[148:151], v[188:191], v[92:95]
	v_mfma_f32_16x16x32_bf16 v[88:91], v[164:167], v[188:191], v[88:91]
	v_mfma_f32_16x16x32_bf16 v[76:79], v[148:151], v[200:203], v[76:79]
	v_mfma_f32_16x16x32_bf16 v[72:75], v[164:167], v[200:203], v[72:75]
	v_mfma_f32_16x16x32_bf16 v[124:127], v[152:155], v[176:179], v[124:127]
	v_mfma_f32_16x16x32_bf16 v[120:123], v[168:171], v[176:179], v[120:123]
	v_mfma_f32_16x16x32_bf16 v[108:111], v[152:155], v[184:187], v[108:111]
	v_mfma_f32_16x16x32_bf16 v[104:107], v[168:171], v[184:187], v[104:107]
	v_mfma_f32_16x16x32_bf16 v[92:95], v[152:155], v[196:199], v[92:95]
	v_mfma_f32_16x16x32_bf16 v[88:91], v[168:171], v[196:199], v[88:91]
	v_mfma_f32_16x16x32_bf16 v[76:79], v[152:155], v[204:207], v[76:79]
	v_mfma_f32_16x16x32_bf16 v[72:75], v[168:171], v[204:207], v[72:75]
	s_barrier
	s_add_i32 s54, 0, 0x1c000
	s_add_i32 s55, s93, s57
	v_add_u32_e32 v136, s54, v158
	v_lshl_add_u64 v[156:157], v[156:157], 0, s[0:1]
	s_mov_b32 m0, s55
	ds_read_b128 v[208:211], v136
	ds_read_b128 v[212:215], v136 offset:1024
	ds_read_b128 v[216:219], v136 offset:2048
	ds_read_b128 v[220:223], v136 offset:3072
	global_load_lds_dwordx4 v[156:157], off
	v_lshl_add_u64 v[156:157], v[224:225], 0, s[0:1]
	s_add_i32 m0, s55, 0x2000
	s_nop 0
	global_load_lds_dwordx4 v[156:157], off
	s_barrier
	s_waitcnt lgkmcnt(0)
	v_mfma_f32_16x16x32_bf16 v[116:119], v[208:211], v[172:175], v[116:119]
	v_mfma_f32_16x16x32_bf16 v[112:115], v[216:219], v[172:175], v[112:115]
	v_mfma_f32_16x16x32_bf16 v[100:103], v[208:211], v[180:183], v[100:103]
	v_mfma_f32_16x16x32_bf16 v[96:99], v[216:219], v[180:183], v[96:99]
	v_mfma_f32_16x16x32_bf16 v[84:87], v[208:211], v[188:191], v[84:87]
	v_mfma_f32_16x16x32_bf16 v[80:83], v[216:219], v[188:191], v[80:83]
	v_mfma_f32_16x16x32_bf16 v[68:71], v[208:211], v[200:203], v[68:71]
	v_mfma_f32_16x16x32_bf16 v[64:67], v[216:219], v[200:203], v[64:67]
	v_mfma_f32_16x16x32_bf16 v[116:119], v[212:215], v[176:179], v[116:119]
	v_mfma_f32_16x16x32_bf16 v[112:115], v[220:223], v[176:179], v[112:115]
	v_mfma_f32_16x16x32_bf16 v[100:103], v[212:215], v[184:187], v[100:103]
	v_mfma_f32_16x16x32_bf16 v[96:99], v[220:223], v[184:187], v[96:99]
	v_mfma_f32_16x16x32_bf16 v[84:87], v[212:215], v[196:199], v[84:87]
	v_mfma_f32_16x16x32_bf16 v[80:83], v[220:223], v[196:199], v[80:83]
	v_mfma_f32_16x16x32_bf16 v[68:71], v[212:215], v[204:207], v[68:71]
	v_mfma_f32_16x16x32_bf16 v[64:67], v[220:223], v[204:207], v[64:67]
	s_mov_b32 m0, s65
	v_lshl_add_u64 v[156:157], v[226:227], 0, s[0:1]
	s_barrier
	ds_read_b128 v[172:175], v160 offset:49152
	ds_read_b128 v[176:179], v160 offset:50176
	ds_read_b128 v[180:183], v160 offset:51200
	ds_read_b128 v[184:187], v160 offset:52224
	ds_read_b128 v[188:191], v160 offset:53248
	ds_read_b128 v[196:199], v160 offset:54272
	ds_read_b128 v[200:203], v160 offset:55296
	ds_read_b128 v[204:207], v160 offset:56320
	global_load_lds_dwordx4 v[156:157], off
	v_lshl_add_u64 v[156:157], v[228:229], 0, s[0:1]
	s_mov_b32 m0, s66
	s_nop 0
	global_load_lds_dwordx4 v[156:157], off
	s_barrier
	s_waitcnt lgkmcnt(0)
	v_mfma_f32_16x16x32_bf16 v[60:63], v[148:151], v[172:175], v[60:63]
	v_mfma_f32_16x16x32_bf16 v[56:59], v[164:167], v[172:175], v[56:59]
	v_mfma_f32_16x16x32_bf16 v[44:47], v[148:151], v[180:183], v[44:47]
	v_mfma_f32_16x16x32_bf16 v[40:43], v[164:167], v[180:183], v[40:43]
	v_mfma_f32_16x16x32_bf16 v[28:31], v[148:151], v[188:191], v[28:31]
	v_mfma_f32_16x16x32_bf16 v[24:27], v[164:167], v[188:191], v[24:27]
	v_mfma_f32_16x16x32_bf16 v[12:15], v[148:151], v[200:203], v[12:15]
	v_mfma_f32_16x16x32_bf16 v[8:11], v[164:167], v[200:203], v[8:11]
	v_mfma_f32_16x16x32_bf16 v[60:63], v[152:155], v[176:179], v[60:63]
	v_mfma_f32_16x16x32_bf16 v[56:59], v[168:171], v[176:179], v[56:59]
	v_mfma_f32_16x16x32_bf16 v[44:47], v[152:155], v[184:187], v[44:47]
	v_mfma_f32_16x16x32_bf16 v[40:43], v[168:171], v[184:187], v[40:43]
	v_mfma_f32_16x16x32_bf16 v[28:31], v[152:155], v[196:199], v[28:31]
	v_mfma_f32_16x16x32_bf16 v[24:27], v[168:171], v[196:199], v[24:27]
	v_mfma_f32_16x16x32_bf16 v[12:15], v[152:155], v[204:207], v[12:15]
	v_mfma_f32_16x16x32_bf16 v[8:11], v[168:171], v[204:207], v[8:11]
	s_barrier
	s_add_u32 s52, s52, 0x10080
	s_addc_u32 s53, s53, 0
	s_add_i32 s54, s54, s57
	v_lshl_add_u64 v[148:149], s[52:53], 0, v[130:131]
	s_mov_b32 m0, s54
	s_nop 0
	global_load_lds_dwordx4 v[148:149], off
	v_lshl_add_u64 v[148:149], s[52:53], 0, v[134:135]
	s_add_i32 m0, s54, 0x2000
	s_nop 0
	global_load_lds_dwordx4 v[148:149], off
	s_waitcnt vmcnt(6)
	s_barrier
	v_mfma_f32_16x16x32_bf16 v[52:55], v[208:211], v[172:175], v[52:55]
	v_mfma_f32_16x16x32_bf16 v[48:51], v[216:219], v[172:175], v[48:51]
	v_mfma_f32_16x16x32_bf16 v[36:39], v[208:211], v[180:183], v[36:39]
	v_mfma_f32_16x16x32_bf16 v[32:35], v[216:219], v[180:183], v[32:35]
	v_mfma_f32_16x16x32_bf16 v[20:23], v[208:211], v[188:191], v[20:23]
	v_mfma_f32_16x16x32_bf16 v[16:19], v[216:219], v[188:191], v[16:19]
	v_mfma_f32_16x16x32_bf16 v[4:7], v[208:211], v[200:203], v[4:7]
	v_mfma_f32_16x16x32_bf16 v[0:3], v[216:219], v[200:203], v[0:3]
	v_mfma_f32_16x16x32_bf16 v[52:55], v[212:215], v[176:179], v[52:55]
	v_mfma_f32_16x16x32_bf16 v[48:51], v[220:223], v[176:179], v[48:51]
	v_mfma_f32_16x16x32_bf16 v[36:39], v[212:215], v[184:187], v[36:39]
	v_mfma_f32_16x16x32_bf16 v[32:35], v[220:223], v[184:187], v[32:35]
	v_mfma_f32_16x16x32_bf16 v[20:23], v[212:215], v[196:199], v[20:23]
	v_mfma_f32_16x16x32_bf16 v[16:19], v[220:223], v[196:199], v[16:19]
	v_mfma_f32_16x16x32_bf16 v[4:7], v[212:215], v[204:207], v[4:7]
	v_mfma_f32_16x16x32_bf16 v[0:3], v[220:223], v[204:207], v[0:3]
	s_add_i32 s92, s92, 2
	s_add_u32 s50, s50, 0x100
	s_addc_u32 s51, s51, 0
	s_add_u32 s45, s45, 0x100
	s_addc_u32 s91, s91, 0
	s_cmp_gt_u32 s92, 13
	s_barrier
	s_cbranch_scc0 .LBB0_178
	v_lshl_add_u32 v148, s12, 8, v139
	v_and_b32_e32 v149, 24, v138
	s_lshl_b32 s11, s10, 8
	s_or_b32 s11, s11, s87
	s_cmp_gt_i32 s10, 11
	s_cbranch_scc1 .Le1_gates
	s_lshr_b32 s13, s10, 1
	s_lshl_b32 s50, s13, 25
	s_add_u32 s50, s20, s50
	s_addc_u32 s51, s21, 0
	s_bfe_u32 s17, s11, 0x30006
	v_ashrrev_i32_e32 v150, 8, v148
	v_and_or_b32 v150, v150, -8, s17
	v_mov_b32_e32 v151, 0
	v_lshlrev_b64 v[150:151], 18, v[150:151]
	v_lshlrev_b32_e32 v136, 7, v148
	v_and_b32_e32 v136, 0x3ff80, v136
	v_lshl_add_u32 v136, v149, 1, v136
	v_lshl_add_u64 v[150:151], v[150:151], 0, v[136:137]
	v_lshl_add_u64 v[150:151], v[150:151], 0, s[50:51]
	s_movk_i32 s11, 0x800
	s_movk_i32 s17, 0x2800
	s_branch .Le1_addr

.LBB0_1092:
	s_ashr_i32 s37, s36, 31
	v_cmp_lt_i64_e32 vcc, s[0:1], v[142:143]
	s_lshl_b64 s[0:1], s[36:37], 19
	s_add_u32 s38, s68, s0
	s_addc_u32 s39, s69, s1
	s_and_b64 s[0:1], vcc, exec
	s_cselect_b32 s37, s39, s45
	s_cselect_b32 s60, s38, s44
	s_ashr_i32 s13, s12, 31
	s_lshl_b64 s[0:1], s[12:13], 19
	s_add_u32 s40, s70, s0
	s_addc_u32 s41, s71, s1
	s_and_b64 s[0:1], vcc, exec
	s_cselect_b32 s13, s41, s43
	s_cselect_b32 s61, s40, s42
	s_add_u32 s0, s44, 0x40080
	s_addc_u32 s1, s45, 0
	s_add_u32 s62, s42, 0x100
	s_addc_u32 s63, s43, 0
	s_mov_b32 s64, -2
	ds_read_b128 v[146:149], v167
	ds_read_b128 v[150:153], v167 offset:1024
	ds_read_b128 v[178:181], v167 offset:2048
	ds_read_b128 v[182:185], v167 offset:3072
	s_add_u32 s28, s0, 0xfffc0080
	s_addc_u32 s29, s1, -1
	s_cmp_eq_u32 s64, 12
	s_cselect_b32 s45, s37, s29
	s_cselect_b32 s44, s60, s28
	s_cselect_b32 s43, s13, s63
	s_cselect_b32 s42, s61, s62
	v_lshl_add_u64 v[156:157], s[0:1], 0, v[138:139]
	s_add_i32 m0, s47, 0xc000
	ds_read_b128 v[186:189], v171
	ds_read_b128 v[196:199], v171 offset:1024
	ds_read_b128 v[200:203], v171 offset:2048
	ds_read_b128 v[204:207], v171 offset:3072
	ds_read_b128 v[208:211], v171 offset:4096
	ds_read_b128 v[212:215], v171 offset:5120
	ds_read_b128 v[216:219], v171 offset:6144
	ds_read_b128 v[220:223], v171 offset:7168
	global_load_lds_dwordx4 v[156:157], off
	v_lshl_add_u64 v[156:157], s[0:1], 0, v[140:141]
	s_add_i32 m0, s47, 0xe000
	s_nop 0
	global_load_lds_dwordx4 v[156:157], off
	s_waitcnt lgkmcnt(8)
	s_barrier
	s_waitcnt lgkmcnt(0)
	v_mfma_f32_16x16x32_bf16 v[124:127], v[146:149], v[186:189], 0
	v_mfma_f32_16x16x32_bf16 v[120:123], v[178:181], v[186:189], 0
	v_mfma_f32_16x16x32_bf16 v[108:111], v[146:149], v[200:203], 0
	v_mfma_f32_16x16x32_bf16 v[104:107], v[178:181], v[200:203], 0
	v_mfma_f32_16x16x32_bf16 v[92:95], v[146:149], v[208:211], 0
	v_mfma_f32_16x16x32_bf16 v[88:91], v[178:181], v[208:211], 0
	v_mfma_f32_16x16x32_bf16 v[76:79], v[146:149], v[216:219], 0
	v_mfma_f32_16x16x32_bf16 v[72:75], v[178:181], v[216:219], 0
	v_mfma_f32_16x16x32_bf16 v[124:127], v[150:153], v[196:199], v[124:127]
	v_mfma_f32_16x16x32_bf16 v[120:123], v[182:185], v[196:199], v[120:123]
	v_mfma_f32_16x16x32_bf16 v[108:111], v[150:153], v[204:207], v[108:111]
	v_mfma_f32_16x16x32_bf16 v[104:107], v[182:185], v[204:207], v[104:107]
	v_mfma_f32_16x16x32_bf16 v[92:95], v[150:153], v[212:215], v[92:95]
	v_mfma_f32_16x16x32_bf16 v[88:91], v[182:185], v[212:215], v[88:91]
	v_mfma_f32_16x16x32_bf16 v[76:79], v[150:153], v[220:223], v[76:79]
	v_mfma_f32_16x16x32_bf16 v[72:75], v[182:185], v[220:223], v[72:75]
	s_barrier
	s_add_i32 s28, s56, s11
	v_lshl_add_u64 v[156:157], s[42:43], 0, v[132:133]
	s_mov_b32 m0, s28
	ds_read_b128 v[224:227], v175
	ds_read_b128 v[228:231], v175 offset:1024
	ds_read_b128 v[232:235], v175 offset:2048
	ds_read_b128 v[236:239], v175 offset:3072
	global_load_lds_dwordx4 v[156:157], off
	v_lshl_add_u64 v[160:161], s[42:43], 0, v[128:129]
	s_add_i32 m0, s28, 0x2000
	s_nop 0
	global_load_lds_dwordx4 v[160:161], off
	s_barrier
	s_waitcnt lgkmcnt(0)
	v_mfma_f32_16x16x32_bf16 v[116:119], v[224:227], v[186:189], 0
	v_mfma_f32_16x16x32_bf16 v[112:115], v[232:235], v[186:189], 0
	v_mfma_f32_16x16x32_bf16 v[100:103], v[224:227], v[200:203], 0
	v_mfma_f32_16x16x32_bf16 v[96:99], v[232:235], v[200:203], 0
	v_mfma_f32_16x16x32_bf16 v[84:87], v[224:227], v[208:211], 0
	v_mfma_f32_16x16x32_bf16 v[80:83], v[232:235], v[208:211], 0
	v_mfma_f32_16x16x32_bf16 v[68:71], v[224:227], v[216:219], 0
	v_mfma_f32_16x16x32_bf16 v[64:67], v[232:235], v[216:219], 0
	v_mfma_f32_16x16x32_bf16 v[116:119], v[228:231], v[196:199], v[116:119]
	v_mfma_f32_16x16x32_bf16 v[112:115], v[236:239], v[196:199], v[112:115]
	v_mfma_f32_16x16x32_bf16 v[100:103], v[228:231], v[204:207], v[100:103]
	v_mfma_f32_16x16x32_bf16 v[96:99], v[236:239], v[204:207], v[96:99]
	v_mfma_f32_16x16x32_bf16 v[84:87], v[228:231], v[212:215], v[84:87]
	v_mfma_f32_16x16x32_bf16 v[80:83], v[236:239], v[212:215], v[80:83]
	v_mfma_f32_16x16x32_bf16 v[68:71], v[228:231], v[220:223], v[68:71]
	v_mfma_f32_16x16x32_bf16 v[64:67], v[236:239], v[220:223], v[64:67]
	s_mov_b32 m0, s47
	v_lshl_add_u64 v[164:165], s[44:45], 0, v[134:135]
	s_barrier
	ds_read_b128 v[186:189], v171 offset:16384
	ds_read_b128 v[196:199], v171 offset:17408
	ds_read_b128 v[200:203], v171 offset:18432
	ds_read_b128 v[204:207], v171 offset:19456
	ds_read_b128 v[208:211], v171 offset:20480
	ds_read_b128 v[212:215], v171 offset:21504
	ds_read_b128 v[216:219], v171 offset:22528
	ds_read_b128 v[220:223], v171 offset:23552
	global_load_lds_dwordx4 v[164:165], off
	v_lshl_add_u64 v[168:169], s[44:45], 0, v[130:131]
	s_mov_b32 m0, s48
	s_nop 0
	global_load_lds_dwordx4 v[168:169], off
	s_barrier
	s_waitcnt lgkmcnt(0)
	v_mfma_f32_16x16x32_bf16 v[60:63], v[146:149], v[186:189], 0
	v_mfma_f32_16x16x32_bf16 v[56:59], v[178:181], v[186:189], 0
	v_mfma_f32_16x16x32_bf16 v[44:47], v[146:149], v[200:203], 0
	v_mfma_f32_16x16x32_bf16 v[40:43], v[178:181], v[200:203], 0
	v_mfma_f32_16x16x32_bf16 v[28:31], v[146:149], v[208:211], 0
	v_mfma_f32_16x16x32_bf16 v[24:27], v[178:181], v[208:211], 0
	v_mfma_f32_16x16x32_bf16 v[12:15], v[146:149], v[216:219], 0
	v_mfma_f32_16x16x32_bf16 v[8:11], v[178:181], v[216:219], 0
	v_mfma_f32_16x16x32_bf16 v[60:63], v[150:153], v[196:199], v[60:63]
	v_mfma_f32_16x16x32_bf16 v[56:59], v[182:185], v[196:199], v[56:59]
	v_mfma_f32_16x16x32_bf16 v[44:47], v[150:153], v[204:207], v[44:47]
	v_mfma_f32_16x16x32_bf16 v[40:43], v[182:185], v[204:207], v[40:43]
	v_mfma_f32_16x16x32_bf16 v[28:31], v[150:153], v[212:215], v[28:31]
	v_mfma_f32_16x16x32_bf16 v[24:27], v[182:185], v[212:215], v[24:27]
	v_mfma_f32_16x16x32_bf16 v[12:15], v[150:153], v[220:223], v[12:15]
	v_mfma_f32_16x16x32_bf16 v[8:11], v[182:185], v[220:223], v[8:11]
	s_barrier
	s_add_u32 s66, s42, 0x40000
	s_addc_u32 s67, s43, 0
	s_add_i32 s28, s57, s11
	v_lshl_add_u64 v[146:147], s[66:67], 0, v[132:133]
	s_mov_b32 m0, s28
	s_nop 0
	global_load_lds_dwordx4 v[146:147], off
	v_lshl_add_u64 v[146:147], s[66:67], 0, v[128:129]
	s_add_i32 m0, s28, 0x2000
	s_nop 0
	global_load_lds_dwordx4 v[146:147], off
	s_waitcnt vmcnt(6)
	s_barrier
	v_mfma_f32_16x16x32_bf16 v[52:55], v[224:227], v[186:189], 0
	v_mfma_f32_16x16x32_bf16 v[48:51], v[232:235], v[186:189], 0
	v_mfma_f32_16x16x32_bf16 v[36:39], v[224:227], v[200:203], 0
	v_mfma_f32_16x16x32_bf16 v[32:35], v[232:235], v[200:203], 0
	v_mfma_f32_16x16x32_bf16 v[20:23], v[224:227], v[208:211], 0
	v_mfma_f32_16x16x32_bf16 v[16:19], v[232:235], v[208:211], 0
	v_mfma_f32_16x16x32_bf16 v[4:7], v[224:227], v[216:219], 0
	v_mfma_f32_16x16x32_bf16 v[0:3], v[232:235], v[216:219], 0
	v_mfma_f32_16x16x32_bf16 v[52:55], v[228:231], v[196:199], v[52:55]
	v_mfma_f32_16x16x32_bf16 v[48:51], v[236:239], v[196:199], v[48:51]
	v_mfma_f32_16x16x32_bf16 v[36:39], v[228:231], v[204:207], v[36:39]
	v_mfma_f32_16x16x32_bf16 v[32:35], v[236:239], v[204:207], v[32:35]
	v_mfma_f32_16x16x32_bf16 v[20:23], v[228:231], v[212:215], v[20:23]
	v_mfma_f32_16x16x32_bf16 v[16:19], v[236:239], v[212:215], v[16:19]
	v_mfma_f32_16x16x32_bf16 v[4:7], v[228:231], v[220:223], v[4:7]
	v_mfma_f32_16x16x32_bf16 v[0:3], v[236:239], v[220:223], v[0:3]
	s_add_i32 s28, 0, 0x18000
	v_add_u32_e32 v154, s28, v159
	s_barrier
	ds_read_b128 v[146:149], v154
	ds_read_b128 v[150:153], v154 offset:1024
	ds_read_b128 v[178:181], v154 offset:2048
	ds_read_b128 v[182:185], v154 offset:3072
	s_add_u32 s44, s44, 0x40000
	s_addc_u32 s45, s45, 0
	s_mov_b32 m0, s49
	v_lshl_add_u64 v[172:173], s[44:45], 0, v[134:135]
	ds_read_b128 v[186:189], v171 offset:32768
	ds_read_b128 v[196:199], v171 offset:33792
	ds_read_b128 v[200:203], v171 offset:34816
	ds_read_b128 v[204:207], v171 offset:35840
	ds_read_b128 v[208:211], v171 offset:36864
	ds_read_b128 v[212:215], v171 offset:37888
	ds_read_b128 v[216:219], v171 offset:38912
	ds_read_b128 v[220:223], v171 offset:39936
	global_load_lds_dwordx4 v[172:173], off
	v_lshl_add_u64 v[172:173], s[44:45], 0, v[130:131]
	s_mov_b32 m0, s50
	s_nop 0
	global_load_lds_dwordx4 v[172:173], off
	s_waitcnt lgkmcnt(8)
	s_barrier
	s_waitcnt lgkmcnt(0)
	v_mfma_f32_16x16x32_bf16 v[124:127], v[146:149], v[186:189], v[124:127]
	v_mfma_f32_16x16x32_bf16 v[120:123], v[178:181], v[186:189], v[120:123]
	v_mfma_f32_16x16x32_bf16 v[108:111], v[146:149], v[200:203], v[108:111]
	v_mfma_f32_16x16x32_bf16 v[104:107], v[178:181], v[200:203], v[104:107]
	v_mfma_f32_16x16x32_bf16 v[92:95], v[146:149], v[208:211], v[92:95]
	v_mfma_f32_16x16x32_bf16 v[88:91], v[178:181], v[208:211], v[88:91]
	v_mfma_f32_16x16x32_bf16 v[76:79], v[146:149], v[216:219], v[76:79]
	v_mfma_f32_16x16x32_bf16 v[72:75], v[178:181], v[216:219], v[72:75]
	v_mfma_f32_16x16x32_bf16 v[124:127], v[150:153], v[196:199], v[124:127]
	v_mfma_f32_16x16x32_bf16 v[120:123], v[182:185], v[196:199], v[120:123]
	v_mfma_f32_16x16x32_bf16 v[108:111], v[150:153], v[204:207], v[108:111]
	v_mfma_f32_16x16x32_bf16 v[104:107], v[182:185], v[204:207], v[104:107]
	v_mfma_f32_16x16x32_bf16 v[92:95], v[150:153], v[212:215], v[92:95]
	v_mfma_f32_16x16x32_bf16 v[88:91], v[182:185], v[212:215], v[88:91]
	v_mfma_f32_16x16x32_bf16 v[76:79], v[150:153], v[220:223], v[76:79]
	v_mfma_f32_16x16x32_bf16 v[72:75], v[182:185], v[220:223], v[72:75]
	s_barrier
	s_add_i32 s29, 0, 0x1c000
	s_add_i32 s28, s28, s11
	v_add_u32_e32 v154, s29, v159
	v_lshl_add_u64 v[156:157], v[156:157], 0, s[6:7]
	s_mov_b32 m0, s28
	ds_read_b128 v[224:227], v154
	ds_read_b128 v[228:231], v154 offset:1024
	ds_read_b128 v[232:235], v154 offset:2048
	ds_read_b128 v[236:239], v154 offset:3072
	global_load_lds_dwordx4 v[156:157], off
	v_lshl_add_u64 v[156:157], v[160:161], 0, s[6:7]
	s_add_i32 m0, s28, 0x2000
	s_nop 0
	global_load_lds_dwordx4 v[156:157], off
	s_barrier
	s_waitcnt lgkmcnt(0)
	v_mfma_f32_16x16x32_bf16 v[116:119], v[224:227], v[186:189], v[116:119]
	v_mfma_f32_16x16x32_bf16 v[112:115], v[232:235], v[186:189], v[112:115]
	v_mfma_f32_16x16x32_bf16 v[100:103], v[224:227], v[200:203], v[100:103]
	v_mfma_f32_16x16x32_bf16 v[96:99], v[232:235], v[200:203], v[96:99]
	v_mfma_f32_16x16x32_bf16 v[84:87], v[224:227], v[208:211], v[84:87]
	v_mfma_f32_16x16x32_bf16 v[80:83], v[232:235], v[208:211], v[80:83]
	v_mfma_f32_16x16x32_bf16 v[68:71], v[224:227], v[216:219], v[68:71]
	v_mfma_f32_16x16x32_bf16 v[64:67], v[232:235], v[216:219], v[64:67]
	v_mfma_f32_16x16x32_bf16 v[116:119], v[228:231], v[196:199], v[116:119]
	v_mfma_f32_16x16x32_bf16 v[112:115], v[236:239], v[196:199], v[112:115]
	v_mfma_f32_16x16x32_bf16 v[100:103], v[228:231], v[204:207], v[100:103]
	v_mfma_f32_16x16x32_bf16 v[96:99], v[236:239], v[204:207], v[96:99]
	v_mfma_f32_16x16x32_bf16 v[84:87], v[228:231], v[212:215], v[84:87]
	v_mfma_f32_16x16x32_bf16 v[80:83], v[236:239], v[212:215], v[80:83]
	v_mfma_f32_16x16x32_bf16 v[68:71], v[228:231], v[220:223], v[68:71]
	v_mfma_f32_16x16x32_bf16 v[64:67], v[236:239], v[220:223], v[64:67]
	s_mov_b32 m0, s53
	v_lshl_add_u64 v[156:157], v[164:165], 0, s[6:7]
	s_barrier
	ds_read_b128 v[186:189], v171 offset:49152
	ds_read_b128 v[196:199], v171 offset:50176
	ds_read_b128 v[200:203], v171 offset:51200
	ds_read_b128 v[204:207], v171 offset:52224
	ds_read_b128 v[208:211], v171 offset:53248
	ds_read_b128 v[212:215], v171 offset:54272
	ds_read_b128 v[216:219], v171 offset:55296
	ds_read_b128 v[220:223], v171 offset:56320
	global_load_lds_dwordx4 v[156:157], off
	v_lshl_add_u64 v[156:157], v[168:169], 0, s[6:7]
	s_mov_b32 m0, s54
	s_nop 0
	global_load_lds_dwordx4 v[156:157], off
	s_barrier
	s_waitcnt lgkmcnt(0)
	v_mfma_f32_16x16x32_bf16 v[60:63], v[146:149], v[186:189], v[60:63]
	v_mfma_f32_16x16x32_bf16 v[56:59], v[178:181], v[186:189], v[56:59]
	v_mfma_f32_16x16x32_bf16 v[44:47], v[146:149], v[200:203], v[44:47]
	v_mfma_f32_16x16x32_bf16 v[40:43], v[178:181], v[200:203], v[40:43]
	v_mfma_f32_16x16x32_bf16 v[28:31], v[146:149], v[208:211], v[28:31]
	v_mfma_f32_16x16x32_bf16 v[24:27], v[178:181], v[208:211], v[24:27]
	v_mfma_f32_16x16x32_bf16 v[12:15], v[146:149], v[216:219], v[12:15]
	v_mfma_f32_16x16x32_bf16 v[8:11], v[178:181], v[216:219], v[8:11]
	v_mfma_f32_16x16x32_bf16 v[60:63], v[150:153], v[196:199], v[60:63]
	v_mfma_f32_16x16x32_bf16 v[56:59], v[182:185], v[196:199], v[56:59]
	v_mfma_f32_16x16x32_bf16 v[44:47], v[150:153], v[204:207], v[44:47]
	v_mfma_f32_16x16x32_bf16 v[40:43], v[182:185], v[204:207], v[40:43]
	v_mfma_f32_16x16x32_bf16 v[28:31], v[150:153], v[212:215], v[28:31]
	v_mfma_f32_16x16x32_bf16 v[24:27], v[182:185], v[212:215], v[24:27]
	v_mfma_f32_16x16x32_bf16 v[12:15], v[150:153], v[220:223], v[12:15]
	v_mfma_f32_16x16x32_bf16 v[8:11], v[182:185], v[220:223], v[8:11]
	s_barrier
	s_add_u32 s42, s42, 0x40080
	s_addc_u32 s43, s43, 0
	s_add_i32 s28, s29, s11
	v_lshl_add_u64 v[146:147], s[42:43], 0, v[132:133]
	s_mov_b32 m0, s28
	s_nop 0
	global_load_lds_dwordx4 v[146:147], off
	v_lshl_add_u64 v[146:147], s[42:43], 0, v[128:129]
	s_add_i32 m0, s28, 0x2000
	s_nop 0
	global_load_lds_dwordx4 v[146:147], off
	s_waitcnt vmcnt(6)
	s_barrier
	v_mfma_f32_16x16x32_bf16 v[52:55], v[224:227], v[186:189], v[52:55]
	v_mfma_f32_16x16x32_bf16 v[48:51], v[232:235], v[186:189], v[48:51]
	v_mfma_f32_16x16x32_bf16 v[36:39], v[224:227], v[200:203], v[36:39]
	v_mfma_f32_16x16x32_bf16 v[32:35], v[232:235], v[200:203], v[32:35]
	v_mfma_f32_16x16x32_bf16 v[20:23], v[224:227], v[208:211], v[20:23]
	v_mfma_f32_16x16x32_bf16 v[16:19], v[232:235], v[208:211], v[16:19]
	v_mfma_f32_16x16x32_bf16 v[4:7], v[224:227], v[216:219], v[4:7]
	v_mfma_f32_16x16x32_bf16 v[0:3], v[232:235], v[216:219], v[0:3]
	v_mfma_f32_16x16x32_bf16 v[52:55], v[228:231], v[196:199], v[52:55]
	v_mfma_f32_16x16x32_bf16 v[48:51], v[236:239], v[196:199], v[48:51]
	v_mfma_f32_16x16x32_bf16 v[36:39], v[228:231], v[204:207], v[36:39]
	v_mfma_f32_16x16x32_bf16 v[32:35], v[236:239], v[204:207], v[32:35]
	v_mfma_f32_16x16x32_bf16 v[20:23], v[228:231], v[212:215], v[20:23]
	v_mfma_f32_16x16x32_bf16 v[16:19], v[236:239], v[212:215], v[16:19]
	v_mfma_f32_16x16x32_bf16 v[4:7], v[228:231], v[220:223], v[4:7]
	v_mfma_f32_16x16x32_bf16 v[0:3], v[236:239], v[220:223], v[0:3]
	s_add_i32 s64, s64, 2
	s_add_u32 s0, s0, 0x100
	s_addc_u32 s1, s1, 0
	s_add_u32 s62, s62, 0x100
	s_addc_u32 s63, s63, 0
	s_cmp_gt_u32 s64, 13
	s_barrier
	s_cbranch_scc0 .LBB0_1093
.LBB0_1093:
	ds_read_b128 v[146:149], v167
	ds_read_b128 v[150:153], v167 offset:1024
	ds_read_b128 v[178:181], v167 offset:2048
	ds_read_b128 v[182:185], v167 offset:3072
	s_add_u32 s28, s0, 0xfffc0080
	s_addc_u32 s29, s1, -1
	s_cmp_eq_u32 s64, 12
	s_cselect_b32 s45, s37, s29
	s_cselect_b32 s44, s60, s28
	s_cselect_b32 s43, s13, s63
	s_cselect_b32 s42, s61, s62
	v_lshl_add_u64 v[156:157], s[0:1], 0, v[138:139]
	s_add_i32 m0, s47, 0xc000
	ds_read_b128 v[186:189], v171
	ds_read_b128 v[196:199], v171 offset:1024
	ds_read_b128 v[200:203], v171 offset:2048
	ds_read_b128 v[204:207], v171 offset:3072
	ds_read_b128 v[208:211], v171 offset:4096
	ds_read_b128 v[212:215], v171 offset:5120
	ds_read_b128 v[216:219], v171 offset:6144
	ds_read_b128 v[220:223], v171 offset:7168
	global_load_lds_dwordx4 v[156:157], off
	v_lshl_add_u64 v[156:157], s[0:1], 0, v[140:141]
	s_add_i32 m0, s47, 0xe000
	s_nop 0
	global_load_lds_dwordx4 v[156:157], off
	s_waitcnt lgkmcnt(8)
	s_barrier
	s_waitcnt lgkmcnt(0)
	v_mfma_f32_16x16x32_bf16 v[124:127], v[146:149], v[186:189], v[124:127]
	v_mfma_f32_16x16x32_bf16 v[120:123], v[178:181], v[186:189], v[120:123]
	v_mfma_f32_16x16x32_bf16 v[108:111], v[146:149], v[200:203], v[108:111]
	v_mfma_f32_16x16x32_bf16 v[104:107], v[178:181], v[200:203], v[104:107]
	v_mfma_f32_16x16x32_bf16 v[92:95], v[146:149], v[208:211], v[92:95]
	v_mfma_f32_16x16x32_bf16 v[88:91], v[178:181], v[208:211], v[88:91]
	v_mfma_f32_16x16x32_bf16 v[76:79], v[146:149], v[216:219], v[76:79]
	v_mfma_f32_16x16x32_bf16 v[72:75], v[178:181], v[216:219], v[72:75]
	v_mfma_f32_16x16x32_bf16 v[124:127], v[150:153], v[196:199], v[124:127]
	v_mfma_f32_16x16x32_bf16 v[120:123], v[182:185], v[196:199], v[120:123]
	v_mfma_f32_16x16x32_bf16 v[108:111], v[150:153], v[204:207], v[108:111]
	v_mfma_f32_16x16x32_bf16 v[104:107], v[182:185], v[204:207], v[104:107]
	v_mfma_f32_16x16x32_bf16 v[92:95], v[150:153], v[212:215], v[92:95]
	v_mfma_f32_16x16x32_bf16 v[88:91], v[182:185], v[212:215], v[88:91]
	v_mfma_f32_16x16x32_bf16 v[76:79], v[150:153], v[220:223], v[76:79]
	v_mfma_f32_16x16x32_bf16 v[72:75], v[182:185], v[220:223], v[72:75]
	s_barrier
	s_add_i32 s28, s56, s11
	v_lshl_add_u64 v[156:157], s[42:43], 0, v[132:133]
	s_mov_b32 m0, s28
	ds_read_b128 v[224:227], v175
	ds_read_b128 v[228:231], v175 offset:1024
	ds_read_b128 v[232:235], v175 offset:2048
	ds_read_b128 v[236:239], v175 offset:3072
	global_load_lds_dwordx4 v[156:157], off
	v_lshl_add_u64 v[160:161], s[42:43], 0, v[128:129]
	s_add_i32 m0, s28, 0x2000
	s_nop 0
	global_load_lds_dwordx4 v[160:161], off
	s_barrier
	s_waitcnt lgkmcnt(0)
	v_mfma_f32_16x16x32_bf16 v[116:119], v[224:227], v[186:189], v[116:119]
	v_mfma_f32_16x16x32_bf16 v[112:115], v[232:235], v[186:189], v[112:115]
	v_mfma_f32_16x16x32_bf16 v[100:103], v[224:227], v[200:203], v[100:103]
	v_mfma_f32_16x16x32_bf16 v[96:99], v[232:235], v[200:203], v[96:99]
	v_mfma_f32_16x16x32_bf16 v[84:87], v[224:227], v[208:211], v[84:87]
	v_mfma_f32_16x16x32_bf16 v[80:83], v[232:235], v[208:211], v[80:83]
	v_mfma_f32_16x16x32_bf16 v[68:71], v[224:227], v[216:219], v[68:71]
	v_mfma_f32_16x16x32_bf16 v[64:67], v[232:235], v[216:219], v[64:67]
	v_mfma_f32_16x16x32_bf16 v[116:119], v[228:231], v[196:199], v[116:119]
	v_mfma_f32_16x16x32_bf16 v[112:115], v[236:239], v[196:199], v[112:115]
	v_mfma_f32_16x16x32_bf16 v[100:103], v[228:231], v[204:207], v[100:103]
	v_mfma_f32_16x16x32_bf16 v[96:99], v[236:239], v[204:207], v[96:99]
	v_mfma_f32_16x16x32_bf16 v[84:87], v[228:231], v[212:215], v[84:87]
	v_mfma_f32_16x16x32_bf16 v[80:83], v[236:239], v[212:215], v[80:83]
	v_mfma_f32_16x16x32_bf16 v[68:71], v[228:231], v[220:223], v[68:71]
	v_mfma_f32_16x16x32_bf16 v[64:67], v[236:239], v[220:223], v[64:67]
	s_mov_b32 m0, s47
	v_lshl_add_u64 v[164:165], s[44:45], 0, v[134:135]
	s_barrier
	ds_read_b128 v[186:189], v171 offset:16384
	ds_read_b128 v[196:199], v171 offset:17408
	ds_read_b128 v[200:203], v171 offset:18432
	ds_read_b128 v[204:207], v171 offset:19456
	ds_read_b128 v[208:211], v171 offset:20480
	ds_read_b128 v[212:215], v171 offset:21504
	ds_read_b128 v[216:219], v171 offset:22528
	ds_read_b128 v[220:223], v171 offset:23552
	global_load_lds_dwordx4 v[164:165], off
	v_lshl_add_u64 v[168:169], s[44:45], 0, v[130:131]
	s_mov_b32 m0, s48
	s_nop 0
	global_load_lds_dwordx4 v[168:169], off
	s_barrier
	s_waitcnt lgkmcnt(0)
	v_mfma_f32_16x16x32_bf16 v[60:63], v[146:149], v[186:189], v[60:63]
	v_mfma_f32_16x16x32_bf16 v[56:59], v[178:181], v[186:189], v[56:59]
	v_mfma_f32_16x16x32_bf16 v[44:47], v[146:149], v[200:203], v[44:47]
	v_mfma_f32_16x16x32_bf16 v[40:43], v[178:181], v[200:203], v[40:43]
	v_mfma_f32_16x16x32_bf16 v[28:31], v[146:149], v[208:211], v[28:31]
	v_mfma_f32_16x16x32_bf16 v[24:27], v[178:181], v[208:211], v[24:27]
	v_mfma_f32_16x16x32_bf16 v[12:15], v[146:149], v[216:219], v[12:15]
	v_mfma_f32_16x16x32_bf16 v[8:11], v[178:181], v[216:219], v[8:11]
	v_mfma_f32_16x16x32_bf16 v[60:63], v[150:153], v[196:199], v[60:63]
	v_mfma_f32_16x16x32_bf16 v[56:59], v[182:185], v[196:199], v[56:59]
	v_mfma_f32_16x16x32_bf16 v[44:47], v[150:153], v[204:207], v[44:47]
	v_mfma_f32_16x16x32_bf16 v[40:43], v[182:185], v[204:207], v[40:43]
	v_mfma_f32_16x16x32_bf16 v[28:31], v[150:153], v[212:215], v[28:31]
	v_mfma_f32_16x16x32_bf16 v[24:27], v[182:185], v[212:215], v[24:27]
	v_mfma_f32_16x16x32_bf16 v[12:15], v[150:153], v[220:223], v[12:15]
	v_mfma_f32_16x16x32_bf16 v[8:11], v[182:185], v[220:223], v[8:11]
	s_barrier
	s_add_u32 s66, s42, 0x40000
	s_addc_u32 s67, s43, 0
	s_add_i32 s28, s57, s11
	v_lshl_add_u64 v[146:147], s[66:67], 0, v[132:133]
	s_mov_b32 m0, s28
	s_nop 0
	global_load_lds_dwordx4 v[146:147], off
	v_lshl_add_u64 v[146:147], s[66:67], 0, v[128:129]
	s_add_i32 m0, s28, 0x2000
	s_nop 0
	global_load_lds_dwordx4 v[146:147], off
	s_waitcnt vmcnt(6)
	s_barrier
	v_mfma_f32_16x16x32_bf16 v[52:55], v[224:227], v[186:189], v[52:55]
	v_mfma_f32_16x16x32_bf16 v[48:51], v[232:235], v[186:189], v[48:51]
	v_mfma_f32_16x16x32_bf16 v[36:39], v[224:227], v[200:203], v[36:39]
	v_mfma_f32_16x16x32_bf16 v[32:35], v[232:235], v[200:203], v[32:35]
	v_mfma_f32_16x16x32_bf16 v[20:23], v[224:227], v[208:211], v[20:23]
	v_mfma_f32_16x16x32_bf16 v[16:19], v[232:235], v[208:211], v[16:19]
	v_mfma_f32_16x16x32_bf16 v[4:7], v[224:227], v[216:219], v[4:7]
	v_mfma_f32_16x16x32_bf16 v[0:3], v[232:235], v[216:219], v[0:3]
	v_mfma_f32_16x16x32_bf16 v[52:55], v[228:231], v[196:199], v[52:55]
	v_mfma_f32_16x16x32_bf16 v[48:51], v[236:239], v[196:199], v[48:51]
	v_mfma_f32_16x16x32_bf16 v[36:39], v[228:231], v[204:207], v[36:39]
	v_mfma_f32_16x16x32_bf16 v[32:35], v[236:239], v[204:207], v[32:35]
	v_mfma_f32_16x16x32_bf16 v[20:23], v[228:231], v[212:215], v[20:23]
	v_mfma_f32_16x16x32_bf16 v[16:19], v[236:239], v[212:215], v[16:19]
	v_mfma_f32_16x16x32_bf16 v[4:7], v[228:231], v[220:223], v[4:7]
	v_mfma_f32_16x16x32_bf16 v[0:3], v[236:239], v[220:223], v[0:3]
	s_add_i32 s28, 0, 0x18000
	v_add_u32_e32 v154, s28, v159
	s_barrier
	ds_read_b128 v[146:149], v154
	ds_read_b128 v[150:153], v154 offset:1024
	ds_read_b128 v[178:181], v154 offset:2048
	ds_read_b128 v[182:185], v154 offset:3072
	s_add_u32 s44, s44, 0x40000
	s_addc_u32 s45, s45, 0
	s_mov_b32 m0, s49
	v_lshl_add_u64 v[172:173], s[44:45], 0, v[134:135]
	ds_read_b128 v[186:189], v171 offset:32768
	ds_read_b128 v[196:199], v171 offset:33792
	ds_read_b128 v[200:203], v171 offset:34816
	ds_read_b128 v[204:207], v171 offset:35840
	ds_read_b128 v[208:211], v171 offset:36864
	ds_read_b128 v[212:215], v171 offset:37888
	ds_read_b128 v[216:219], v171 offset:38912
	ds_read_b128 v[220:223], v171 offset:39936
	global_load_lds_dwordx4 v[172:173], off
	v_lshl_add_u64 v[172:173], s[44:45], 0, v[130:131]
	s_mov_b32 m0, s50
	s_nop 0
	global_load_lds_dwordx4 v[172:173], off
	s_waitcnt lgkmcnt(8)
	s_barrier
	s_waitcnt lgkmcnt(0)
	v_mfma_f32_16x16x32_bf16 v[124:127], v[146:149], v[186:189], v[124:127]
	v_mfma_f32_16x16x32_bf16 v[120:123], v[178:181], v[186:189], v[120:123]
	v_mfma_f32_16x16x32_bf16 v[108:111], v[146:149], v[200:203], v[108:111]
	v_mfma_f32_16x16x32_bf16 v[104:107], v[178:181], v[200:203], v[104:107]
	v_mfma_f32_16x16x32_bf16 v[92:95], v[146:149], v[208:211], v[92:95]
	v_mfma_f32_16x16x32_bf16 v[88:91], v[178:181], v[208:211], v[88:91]
	v_mfma_f32_16x16x32_bf16 v[76:79], v[146:149], v[216:219], v[76:79]
	v_mfma_f32_16x16x32_bf16 v[72:75], v[178:181], v[216:219], v[72:75]
	v_mfma_f32_16x16x32_bf16 v[124:127], v[150:153], v[196:199], v[124:127]
	v_mfma_f32_16x16x32_bf16 v[120:123], v[182:185], v[196:199], v[120:123]
	v_mfma_f32_16x16x32_bf16 v[108:111], v[150:153], v[204:207], v[108:111]
	v_mfma_f32_16x16x32_bf16 v[104:107], v[182:185], v[204:207], v[104:107]
	v_mfma_f32_16x16x32_bf16 v[92:95], v[150:153], v[212:215], v[92:95]
	v_mfma_f32_16x16x32_bf16 v[88:91], v[182:185], v[212:215], v[88:91]
	v_mfma_f32_16x16x32_bf16 v[76:79], v[150:153], v[220:223], v[76:79]
	v_mfma_f32_16x16x32_bf16 v[72:75], v[182:185], v[220:223], v[72:75]
	s_barrier
	s_add_i32 s29, 0, 0x1c000
	s_add_i32 s28, s28, s11
	v_add_u32_e32 v154, s29, v159
	v_lshl_add_u64 v[156:157], v[156:157], 0, s[6:7]
	s_mov_b32 m0, s28
	ds_read_b128 v[224:227], v154
	ds_read_b128 v[228:231], v154 offset:1024
	ds_read_b128 v[232:235], v154 offset:2048
	ds_read_b128 v[236:239], v154 offset:3072
	global_load_lds_dwordx4 v[156:157], off
	v_lshl_add_u64 v[156:157], v[160:161], 0, s[6:7]
	s_add_i32 m0, s28, 0x2000
	s_nop 0
	global_load_lds_dwordx4 v[156:157], off
	s_barrier
	s_waitcnt lgkmcnt(0)
	v_mfma_f32_16x16x32_bf16 v[116:119], v[224:227], v[186:189], v[116:119]
	v_mfma_f32_16x16x32_bf16 v[112:115], v[232:235], v[186:189], v[112:115]
	v_mfma_f32_16x16x32_bf16 v[100:103], v[224:227], v[200:203], v[100:103]
	v_mfma_f32_16x16x32_bf16 v[96:99], v[232:235], v[200:203], v[96:99]
	v_mfma_f32_16x16x32_bf16 v[84:87], v[224:227], v[208:211], v[84:87]
	v_mfma_f32_16x16x32_bf16 v[80:83], v[232:235], v[208:211], v[80:83]
	v_mfma_f32_16x16x32_bf16 v[68:71], v[224:227], v[216:219], v[68:71]
	v_mfma_f32_16x16x32_bf16 v[64:67], v[232:235], v[216:219], v[64:67]
	v_mfma_f32_16x16x32_bf16 v[116:119], v[228:231], v[196:199], v[116:119]
	v_mfma_f32_16x16x32_bf16 v[112:115], v[236:239], v[196:199], v[112:115]
	v_mfma_f32_16x16x32_bf16 v[100:103], v[228:231], v[204:207], v[100:103]
	v_mfma_f32_16x16x32_bf16 v[96:99], v[236:239], v[204:207], v[96:99]
	v_mfma_f32_16x16x32_bf16 v[84:87], v[228:231], v[212:215], v[84:87]
	v_mfma_f32_16x16x32_bf16 v[80:83], v[236:239], v[212:215], v[80:83]
	v_mfma_f32_16x16x32_bf16 v[68:71], v[228:231], v[220:223], v[68:71]
	v_mfma_f32_16x16x32_bf16 v[64:67], v[236:239], v[220:223], v[64:67]
	s_mov_b32 m0, s53
	v_lshl_add_u64 v[156:157], v[164:165], 0, s[6:7]
	s_barrier
	ds_read_b128 v[186:189], v171 offset:49152
	ds_read_b128 v[196:199], v171 offset:50176
	ds_read_b128 v[200:203], v171 offset:51200
	ds_read_b128 v[204:207], v171 offset:52224
	ds_read_b128 v[208:211], v171 offset:53248
	ds_read_b128 v[212:215], v171 offset:54272
	ds_read_b128 v[216:219], v171 offset:55296
	ds_read_b128 v[220:223], v171 offset:56320
	global_load_lds_dwordx4 v[156:157], off
	v_lshl_add_u64 v[156:157], v[168:169], 0, s[6:7]
	s_mov_b32 m0, s54
	s_nop 0
	global_load_lds_dwordx4 v[156:157], off
	s_barrier
	s_waitcnt lgkmcnt(0)
	v_mfma_f32_16x16x32_bf16 v[60:63], v[146:149], v[186:189], v[60:63]
	v_mfma_f32_16x16x32_bf16 v[56:59], v[178:181], v[186:189], v[56:59]
	v_mfma_f32_16x16x32_bf16 v[44:47], v[146:149], v[200:203], v[44:47]
	v_mfma_f32_16x16x32_bf16 v[40:43], v[178:181], v[200:203], v[40:43]
	v_mfma_f32_16x16x32_bf16 v[28:31], v[146:149], v[208:211], v[28:31]
	v_mfma_f32_16x16x32_bf16 v[24:27], v[178:181], v[208:211], v[24:27]
	v_mfma_f32_16x16x32_bf16 v[12:15], v[146:149], v[216:219], v[12:15]
	v_mfma_f32_16x16x32_bf16 v[8:11], v[178:181], v[216:219], v[8:11]
	v_mfma_f32_16x16x32_bf16 v[60:63], v[150:153], v[196:199], v[60:63]
	v_mfma_f32_16x16x32_bf16 v[56:59], v[182:185], v[196:199], v[56:59]
	v_mfma_f32_16x16x32_bf16 v[44:47], v[150:153], v[204:207], v[44:47]
	v_mfma_f32_16x16x32_bf16 v[40:43], v[182:185], v[204:207], v[40:43]
	v_mfma_f32_16x16x32_bf16 v[28:31], v[150:153], v[212:215], v[28:31]
	v_mfma_f32_16x16x32_bf16 v[24:27], v[182:185], v[212:215], v[24:27]
	v_mfma_f32_16x16x32_bf16 v[12:15], v[150:153], v[220:223], v[12:15]
	v_mfma_f32_16x16x32_bf16 v[8:11], v[182:185], v[220:223], v[8:11]
	s_barrier
	s_add_u32 s42, s42, 0x40080
	s_addc_u32 s43, s43, 0
	s_add_i32 s28, s29, s11
	v_lshl_add_u64 v[146:147], s[42:43], 0, v[132:133]
	s_mov_b32 m0, s28
	s_nop 0
	global_load_lds_dwordx4 v[146:147], off
	v_lshl_add_u64 v[146:147], s[42:43], 0, v[128:129]
	s_add_i32 m0, s28, 0x2000
	s_nop 0
	global_load_lds_dwordx4 v[146:147], off
	s_waitcnt vmcnt(6)
	s_barrier
	v_mfma_f32_16x16x32_bf16 v[52:55], v[224:227], v[186:189], v[52:55]
	v_mfma_f32_16x16x32_bf16 v[48:51], v[232:235], v[186:189], v[48:51]
	v_mfma_f32_16x16x32_bf16 v[36:39], v[224:227], v[200:203], v[36:39]
	v_mfma_f32_16x16x32_bf16 v[32:35], v[232:235], v[200:203], v[32:35]
	v_mfma_f32_16x16x32_bf16 v[20:23], v[224:227], v[208:211], v[20:23]
	v_mfma_f32_16x16x32_bf16 v[16:19], v[232:235], v[208:211], v[16:19]
	v_mfma_f32_16x16x32_bf16 v[4:7], v[224:227], v[216:219], v[4:7]
	v_mfma_f32_16x16x32_bf16 v[0:3], v[232:235], v[216:219], v[0:3]
	v_mfma_f32_16x16x32_bf16 v[52:55], v[228:231], v[196:199], v[52:55]
	v_mfma_f32_16x16x32_bf16 v[48:51], v[236:239], v[196:199], v[48:51]
	v_mfma_f32_16x16x32_bf16 v[36:39], v[228:231], v[204:207], v[36:39]
	v_mfma_f32_16x16x32_bf16 v[32:35], v[236:239], v[204:207], v[32:35]
	v_mfma_f32_16x16x32_bf16 v[20:23], v[228:231], v[212:215], v[20:23]
	v_mfma_f32_16x16x32_bf16 v[16:19], v[236:239], v[212:215], v[16:19]
	v_mfma_f32_16x16x32_bf16 v[4:7], v[228:231], v[220:223], v[4:7]
	v_mfma_f32_16x16x32_bf16 v[0:3], v[236:239], v[220:223], v[0:3]
	s_add_i32 s64, s64, 2
	s_add_u32 s0, s0, 0x100
	s_addc_u32 s1, s1, 0
	s_add_u32 s62, s62, 0x100
	s_addc_u32 s63, s63, 0
	s_cmp_gt_u32 s64, 13
	s_barrier
	s_cbranch_scc0 .LBB0_1093
	v_lshl_add_u32 v168, s4, 8, v155
	v_or_b32_e32 v164, 16, v168
	v_or_b32_e32 v160, 32, v168
	v_or_b32_e32 v156, 48, v168
	v_add_u32_e32 v152, 0x80, v168
	v_add_u32_e32 v150, 0x90, v168
	v_add_u32_e32 v148, 0xa0, v168
	v_add_u32_e32 v146, 0xb0, v168
	v_lshl_or_b32 v172, s5, 7, v163
	v_mov_b32_e32 v178, v240
	v_mov_b32_e32 v179, v240
	v_mov_b32_e32 v154, v241
	s_and_b32 s0, s36, 0x7f
	v_lshl_add_u32 v228, s0, 8, v155
	v_mov_b32_e32 v229, 0
	v_lshlrev_b32_e32 v228, 6, v228
	v_lshl_add_u64 v[230:231], v[136:137], 0, v[228:229]
	v_mov_b32_e32 v228, 0x2000
	v_lshl_add_u64 v[232:233], v[230:231], 0, v[228:229]
	global_load_dwordx4 v[216:219], v[230:231], off
	global_load_dwordx4 v[220:223], v[230:231], off offset:1024
	global_load_dwordx4 v[224:227], v[230:231], off offset:2048
	global_load_dwordx4 v[196:199], v[230:231], off offset:3072
	global_load_dwordx4 v[200:203], v[232:233], off
	global_load_dwordx4 v[204:207], v[232:233], off offset:1024
	global_load_dwordx4 v[208:211], v[232:233], off offset:2048
	global_load_dwordx4 v[212:215], v[232:233], off offset:3072
	v_pk_mul_f32 v[124:125], v[124:125], v[178:179] op_sel_hi:[1,0]
	v_pk_mul_f32 v[126:127], v[126:127], v[178:179] op_sel_hi:[1,0]
	v_mul_f32_e32 v147, 0xbfb8aa3b, v124
	v_exp_f32_e32 v147, v147
	v_mul_f32_e32 v149, 0xbfb8aa3b, v125
	v_exp_f32_e32 v149, v149
	v_mul_f32_e32 v151, 0xbfb8aa3b, v127
	v_add_f32_e32 v147, 1.0, v147
	v_rcp_f32_e32 v180, v147
	v_add_f32_e32 v147, 1.0, v149
	v_mul_f32_e32 v149, 0xbfb8aa3b, v126
	v_exp_f32_e32 v149, v149
	v_exp_f32_e32 v151, v151
	v_rcp_f32_e32 v181, v147
	v_pk_mul_f32 v[116:117], v[116:117], v[178:179] op_sel_hi:[1,0]
	v_add_f32_e32 v147, 1.0, v149
	v_rcp_f32_e32 v182, v147
	v_add_f32_e32 v147, 1.0, v151
	v_rcp_f32_e32 v183, v147
	v_pk_mul_f32 v[124:125], v[124:125], v[180:181]
	v_pk_mul_f32 v[120:121], v[120:121], v[178:179] op_sel_hi:[1,0]
	v_pk_mul_f32 v[116:117], v[116:117], v[124:125]
	v_pk_mul_f32 v[124:125], v[126:127], v[182:183]
	v_mul_f32_e32 v126, 0xbfb8aa3b, v120
	v_exp_f32_e32 v126, v126
	v_pk_mul_f32 v[118:119], v[118:119], v[178:179] op_sel_hi:[1,0]
	v_pk_mul_f32 v[122:123], v[122:123], v[178:179] op_sel_hi:[1,0]
	v_pk_mul_f32 v[118:119], v[118:119], v[124:125]
	v_mul_f32_e32 v124, 0xbfb8aa3b, v121
	v_exp_f32_e32 v125, v124
	v_add_f32_e32 v124, 1.0, v126
	v_mul_f32_e32 v126, 0xbfb8aa3b, v122
	v_mul_f32_e32 v127, 0xbfb8aa3b, v123
	v_exp_f32_e32 v126, v126
	v_exp_f32_e32 v127, v127
	v_add_f32_e32 v125, 1.0, v125
	v_rcp_f32_e32 v124, v124
	v_rcp_f32_e32 v125, v125
	v_add_f32_e32 v126, 1.0, v126
	v_add_f32_e32 v127, 1.0, v127
	v_rcp_f32_e32 v126, v126
	v_rcp_f32_e32 v127, v127
	v_pk_mul_f32 v[112:113], v[112:113], v[178:179] op_sel_hi:[1,0]
	v_pk_mul_f32 v[120:121], v[120:121], v[124:125]
	v_pk_mul_f32 v[114:115], v[114:115], v[178:179] op_sel_hi:[1,0]
	v_pk_mul_f32 v[112:113], v[112:113], v[120:121]
	v_pk_mul_f32 v[120:121], v[122:123], v[126:127]
	v_ashrrev_i32_e32 v173, 31, v172
	v_pk_mul_f32 v[114:115], v[114:115], v[120:121]
	v_cvt_pk_bf16_f32 v116, v116, v117
	v_cvt_pk_bf16_f32 v117, v118, v119
	v_cvt_pk_bf16_f32 v118, v112, v113
	v_mov_b64_e32 v[112:113], s[20:21]
	v_cvt_pk_bf16_f32 v119, v114, v115
	v_mad_i64_i32 v[120:121], s[0:1], v168, s59, v[112:113]
	v_lshlrev_b64 v[114:115], 1, v[172:173]
	v_lshl_add_u64 v[120:121], v[120:121], 0, v[114:115]
	v_pk_mul_f32 v[108:109], v[108:109], v[176:177] op_sel_hi:[1,0]
	global_store_dwordx4 v[120:121], v[116:119], off
	v_mul_f32_e32 v122, 0xbfb8aa3b, v108
	v_pk_mul_f32 v[110:111], v[110:111], v[176:177] op_sel_hi:[1,0]
	v_mul_f32_e32 v116, 0xbfb8aa3b, v109
	v_exp_f32_e32 v122, v122
	v_exp_f32_e32 v117, v116
	v_mul_f32_e32 v118, 0xbfb8aa3b, v110
	v_mul_f32_e32 v119, 0xbfb8aa3b, v111
	v_exp_f32_e32 v118, v118
	v_exp_f32_e32 v119, v119
	v_add_f32_e32 v116, 1.0, v122
	v_add_f32_e32 v117, 1.0, v117
	v_rcp_f32_e32 v116, v116
	v_rcp_f32_e32 v117, v117
	v_add_f32_e32 v118, 1.0, v118
	v_add_f32_e32 v119, 1.0, v119
	v_rcp_f32_e32 v118, v118
	v_rcp_f32_e32 v119, v119
	v_pk_mul_f32 v[100:101], v[100:101], v[176:177] op_sel_hi:[1,0]
	v_pk_mul_f32 v[108:109], v[108:109], v[116:117]
	v_pk_mul_f32 v[104:105], v[104:105], v[176:177] op_sel_hi:[1,0]
	v_pk_mul_f32 v[100:101], v[100:101], v[108:109]
	v_pk_mul_f32 v[108:109], v[110:111], v[118:119]
	v_mul_f32_e32 v110, 0xbfb8aa3b, v104
	v_exp_f32_e32 v110, v110
	v_pk_mul_f32 v[102:103], v[102:103], v[176:177] op_sel_hi:[1,0]
	v_pk_mul_f32 v[106:107], v[106:107], v[176:177] op_sel_hi:[1,0]
	v_pk_mul_f32 v[102:103], v[102:103], v[108:109]
	v_mul_f32_e32 v108, 0xbfb8aa3b, v105
	v_exp_f32_e32 v109, v108
	v_add_f32_e32 v108, 1.0, v110
	v_mul_f32_e32 v110, 0xbfb8aa3b, v106
	v_mul_f32_e32 v111, 0xbfb8aa3b, v107
	v_exp_f32_e32 v110, v110
	v_exp_f32_e32 v111, v111
	v_add_f32_e32 v109, 1.0, v109
	v_rcp_f32_e32 v108, v108
	v_rcp_f32_e32 v109, v109
	v_add_f32_e32 v110, 1.0, v110
	v_add_f32_e32 v111, 1.0, v111
	v_rcp_f32_e32 v110, v110
	v_rcp_f32_e32 v111, v111
	v_pk_mul_f32 v[96:97], v[96:97], v[176:177] op_sel_hi:[1,0]
	v_pk_mul_f32 v[104:105], v[104:105], v[108:109]
	v_pk_mul_f32 v[92:93], v[92:93], v[174:175] op_sel_hi:[1,0]
	v_pk_mul_f32 v[104:105], v[96:97], v[104:105]
	v_pk_mul_f32 v[96:97], v[98:99], v[176:177] op_sel_hi:[1,0]
	v_pk_mul_f32 v[98:99], v[106:107], v[110:111]
	v_pk_mul_f32 v[94:95], v[94:95], v[174:175] op_sel_hi:[1,0]
	v_pk_mul_f32 v[106:107], v[96:97], v[98:99]
	v_cvt_pk_bf16_f32 v96, v100, v101
	v_mad_i64_i32 v[100:101], s[0:1], v164, s59, v[112:113]
	v_cvt_pk_bf16_f32 v97, v102, v103
	v_cvt_pk_bf16_f32 v98, v104, v105
	v_cvt_pk_bf16_f32 v99, v106, v107
	v_lshl_add_u64 v[100:101], v[100:101], 0, v[114:115]
	v_mul_f32_e32 v102, 0xbfb8aa3b, v92
	global_store_dwordx4 v[100:101], v[96:99], off
	v_exp_f32_e32 v102, v102
	v_pk_mul_f32 v[84:85], v[84:85], v[174:175] op_sel_hi:[1,0]
	v_mul_f32_e32 v96, 0xbfb8aa3b, v93
	v_exp_f32_e32 v97, v96
	v_mul_f32_e32 v98, 0xbfb8aa3b, v94
	v_mul_f32_e32 v99, 0xbfb8aa3b, v95
	v_exp_f32_e32 v98, v98
	v_exp_f32_e32 v99, v99
	v_add_f32_e32 v96, 1.0, v102
	v_add_f32_e32 v97, 1.0, v97
	v_rcp_f32_e32 v96, v96
	v_rcp_f32_e32 v97, v97
	v_add_f32_e32 v98, 1.0, v98
	v_add_f32_e32 v99, 1.0, v99
	v_rcp_f32_e32 v98, v98
	v_rcp_f32_e32 v99, v99
	v_pk_mul_f32 v[92:93], v[92:93], v[96:97]
	v_pk_mul_f32 v[88:89], v[88:89], v[174:175] op_sel_hi:[1,0]
	v_pk_mul_f32 v[84:85], v[84:85], v[92:93]
	v_pk_mul_f32 v[92:93], v[94:95], v[98:99]
	v_mul_f32_e32 v94, 0xbfb8aa3b, v88
	v_exp_f32_e32 v94, v94
	v_pk_mul_f32 v[86:87], v[86:87], v[174:175] op_sel_hi:[1,0]
	v_pk_mul_f32 v[90:91], v[90:91], v[174:175] op_sel_hi:[1,0]
	v_pk_mul_f32 v[86:87], v[86:87], v[92:93]
	v_mul_f32_e32 v92, 0xbfb8aa3b, v89
	v_exp_f32_e32 v93, v92
	v_add_f32_e32 v92, 1.0, v94
	v_mul_f32_e32 v94, 0xbfb8aa3b, v90
	v_mul_f32_e32 v95, 0xbfb8aa3b, v91
	v_exp_f32_e32 v94, v94
	v_exp_f32_e32 v95, v95
	v_add_f32_e32 v93, 1.0, v93
	v_rcp_f32_e32 v92, v92
	v_rcp_f32_e32 v93, v93
	v_add_f32_e32 v94, 1.0, v94
	v_add_f32_e32 v95, 1.0, v95
	v_rcp_f32_e32 v94, v94
	v_rcp_f32_e32 v95, v95
	v_pk_mul_f32 v[80:81], v[80:81], v[174:175] op_sel_hi:[1,0]
	v_pk_mul_f32 v[88:89], v[88:89], v[92:93]
	v_pk_mul_f32 v[76:77], v[76:77], v[170:171] op_sel_hi:[1,0]
	v_pk_mul_f32 v[88:89], v[80:81], v[88:89]
	v_pk_mul_f32 v[80:81], v[82:83], v[174:175] op_sel_hi:[1,0]
	v_pk_mul_f32 v[82:83], v[90:91], v[94:95]
	v_pk_mul_f32 v[78:79], v[78:79], v[170:171] op_sel_hi:[1,0]
	v_pk_mul_f32 v[90:91], v[80:81], v[82:83]
	v_cvt_pk_bf16_f32 v80, v84, v85
	v_mad_i64_i32 v[84:85], s[0:1], v160, s59, v[112:113]
	v_cvt_pk_bf16_f32 v81, v86, v87
	v_cvt_pk_bf16_f32 v82, v88, v89
	v_cvt_pk_bf16_f32 v83, v90, v91
	v_lshl_add_u64 v[84:85], v[84:85], 0, v[114:115]
	v_mul_f32_e32 v86, 0xbfb8aa3b, v76
	global_store_dwordx4 v[84:85], v[80:83], off
	v_exp_f32_e32 v86, v86
	v_pk_mul_f32 v[68:69], v[68:69], v[170:171] op_sel_hi:[1,0]
	v_mul_f32_e32 v80, 0xbfb8aa3b, v77
	v_exp_f32_e32 v81, v80
	v_mul_f32_e32 v82, 0xbfb8aa3b, v78
	v_mul_f32_e32 v83, 0xbfb8aa3b, v79
	v_exp_f32_e32 v82, v82
	v_exp_f32_e32 v83, v83
	v_add_f32_e32 v80, 1.0, v86
	v_add_f32_e32 v81, 1.0, v81
	v_rcp_f32_e32 v80, v80
	v_rcp_f32_e32 v81, v81
	v_add_f32_e32 v82, 1.0, v82
	v_add_f32_e32 v83, 1.0, v83
	v_rcp_f32_e32 v82, v82
	v_rcp_f32_e32 v83, v83
	v_pk_mul_f32 v[76:77], v[76:77], v[80:81]
	v_pk_mul_f32 v[72:73], v[72:73], v[170:171] op_sel_hi:[1,0]
	v_pk_mul_f32 v[68:69], v[68:69], v[76:77]
	v_pk_mul_f32 v[76:77], v[78:79], v[82:83]
	v_mul_f32_e32 v78, 0xbfb8aa3b, v72
	v_exp_f32_e32 v78, v78
	v_pk_mul_f32 v[70:71], v[70:71], v[170:171] op_sel_hi:[1,0]
	v_pk_mul_f32 v[74:75], v[74:75], v[170:171] op_sel_hi:[1,0]
	v_pk_mul_f32 v[70:71], v[70:71], v[76:77]
	v_mul_f32_e32 v76, 0xbfb8aa3b, v73
	v_exp_f32_e32 v77, v76
	v_add_f32_e32 v76, 1.0, v78
	v_mul_f32_e32 v78, 0xbfb8aa3b, v74
	v_mul_f32_e32 v79, 0xbfb8aa3b, v75
	v_exp_f32_e32 v78, v78
	v_exp_f32_e32 v79, v79
	v_add_f32_e32 v77, 1.0, v77
	v_rcp_f32_e32 v76, v76
	v_rcp_f32_e32 v77, v77
	v_add_f32_e32 v78, 1.0, v78
	v_add_f32_e32 v79, 1.0, v79
	v_rcp_f32_e32 v78, v78
	v_rcp_f32_e32 v79, v79
	v_pk_mul_f32 v[64:65], v[64:65], v[170:171] op_sel_hi:[1,0]
	v_pk_mul_f32 v[72:73], v[72:73], v[76:77]
	v_pk_mul_f32 v[60:61], v[60:61], v[166:167] op_sel_hi:[1,0]
	v_pk_mul_f32 v[72:73], v[64:65], v[72:73]
	v_pk_mul_f32 v[64:65], v[66:67], v[170:171] op_sel_hi:[1,0]
	v_pk_mul_f32 v[66:67], v[74:75], v[78:79]
	v_pk_mul_f32 v[62:63], v[62:63], v[166:167] op_sel_hi:[1,0]
	v_pk_mul_f32 v[74:75], v[64:65], v[66:67]
	v_cvt_pk_bf16_f32 v64, v68, v69
	v_mad_i64_i32 v[68:69], s[0:1], v156, s59, v[112:113]
	v_cvt_pk_bf16_f32 v65, v70, v71
	v_cvt_pk_bf16_f32 v66, v72, v73
	v_cvt_pk_bf16_f32 v67, v74, v75
	v_lshl_add_u64 v[68:69], v[68:69], 0, v[114:115]
	v_mul_f32_e32 v70, 0xbfb8aa3b, v60
	global_store_dwordx4 v[68:69], v[64:67], off
	v_exp_f32_e32 v70, v70
	v_pk_mul_f32 v[52:53], v[52:53], v[166:167] op_sel_hi:[1,0]
	v_mul_f32_e32 v64, 0xbfb8aa3b, v61
	v_exp_f32_e32 v65, v64
	v_mul_f32_e32 v66, 0xbfb8aa3b, v62
	v_mul_f32_e32 v67, 0xbfb8aa3b, v63
	v_exp_f32_e32 v66, v66
	v_exp_f32_e32 v67, v67
	v_add_f32_e32 v64, 1.0, v70
	v_add_f32_e32 v65, 1.0, v65
	v_rcp_f32_e32 v64, v64
	v_rcp_f32_e32 v65, v65
	v_add_f32_e32 v66, 1.0, v66
	v_add_f32_e32 v67, 1.0, v67
	v_rcp_f32_e32 v66, v66
	v_rcp_f32_e32 v67, v67
	v_pk_mul_f32 v[60:61], v[60:61], v[64:65]
	v_pk_mul_f32 v[56:57], v[56:57], v[166:167] op_sel_hi:[1,0]
	v_pk_mul_f32 v[52:53], v[52:53], v[60:61]
	v_pk_mul_f32 v[60:61], v[62:63], v[66:67]
	v_mul_f32_e32 v62, 0xbfb8aa3b, v56
	v_exp_f32_e32 v62, v62
	v_pk_mul_f32 v[54:55], v[54:55], v[166:167] op_sel_hi:[1,0]
	v_pk_mul_f32 v[58:59], v[58:59], v[166:167] op_sel_hi:[1,0]
	v_pk_mul_f32 v[54:55], v[54:55], v[60:61]
	v_mul_f32_e32 v60, 0xbfb8aa3b, v57
	v_exp_f32_e32 v61, v60
	v_add_f32_e32 v60, 1.0, v62
	v_mul_f32_e32 v62, 0xbfb8aa3b, v58
	v_mul_f32_e32 v63, 0xbfb8aa3b, v59
	v_exp_f32_e32 v62, v62
	v_exp_f32_e32 v63, v63
	v_add_f32_e32 v61, 1.0, v61
	v_rcp_f32_e32 v60, v60
	v_rcp_f32_e32 v61, v61
	v_add_f32_e32 v62, 1.0, v62
	v_add_f32_e32 v63, 1.0, v63
	v_rcp_f32_e32 v62, v62
	v_rcp_f32_e32 v63, v63
	v_pk_mul_f32 v[48:49], v[48:49], v[166:167] op_sel_hi:[1,0]
	v_pk_mul_f32 v[56:57], v[56:57], v[60:61]
	v_pk_mul_f32 v[44:45], v[44:45], v[162:163] op_sel_hi:[1,0]
	v_pk_mul_f32 v[56:57], v[48:49], v[56:57]
	v_pk_mul_f32 v[48:49], v[50:51], v[166:167] op_sel_hi:[1,0]
	v_pk_mul_f32 v[50:51], v[58:59], v[62:63]
	v_pk_mul_f32 v[46:47], v[46:47], v[162:163] op_sel_hi:[1,0]
	v_pk_mul_f32 v[58:59], v[48:49], v[50:51]
	v_cvt_pk_bf16_f32 v48, v52, v53
	v_mad_i64_i32 v[52:53], s[0:1], v152, s59, v[112:113]
	v_cvt_pk_bf16_f32 v49, v54, v55
	v_cvt_pk_bf16_f32 v50, v56, v57
	v_cvt_pk_bf16_f32 v51, v58, v59
	v_lshl_add_u64 v[52:53], v[52:53], 0, v[114:115]
	v_mul_f32_e32 v54, 0xbfb8aa3b, v44
	global_store_dwordx4 v[52:53], v[48:51], off
	v_exp_f32_e32 v54, v54
	v_pk_mul_f32 v[36:37], v[36:37], v[162:163] op_sel_hi:[1,0]
	v_mul_f32_e32 v48, 0xbfb8aa3b, v45
	v_exp_f32_e32 v49, v48
	v_mul_f32_e32 v50, 0xbfb8aa3b, v46
	v_mul_f32_e32 v51, 0xbfb8aa3b, v47
	v_exp_f32_e32 v50, v50
	v_exp_f32_e32 v51, v51
	v_add_f32_e32 v48, 1.0, v54
	v_add_f32_e32 v49, 1.0, v49
	v_rcp_f32_e32 v48, v48
	v_rcp_f32_e32 v49, v49
	v_add_f32_e32 v50, 1.0, v50
	v_add_f32_e32 v51, 1.0, v51
	v_rcp_f32_e32 v50, v50
	v_rcp_f32_e32 v51, v51
	v_pk_mul_f32 v[44:45], v[44:45], v[48:49]
	v_pk_mul_f32 v[40:41], v[40:41], v[162:163] op_sel_hi:[1,0]
	v_pk_mul_f32 v[36:37], v[36:37], v[44:45]
	v_pk_mul_f32 v[44:45], v[46:47], v[50:51]
	v_mul_f32_e32 v46, 0xbfb8aa3b, v40
	v_exp_f32_e32 v46, v46
	v_pk_mul_f32 v[38:39], v[38:39], v[162:163] op_sel_hi:[1,0]
	v_pk_mul_f32 v[42:43], v[42:43], v[162:163] op_sel_hi:[1,0]
	v_pk_mul_f32 v[38:39], v[38:39], v[44:45]
	v_mul_f32_e32 v44, 0xbfb8aa3b, v41
	v_exp_f32_e32 v45, v44
	v_add_f32_e32 v44, 1.0, v46
	v_mul_f32_e32 v46, 0xbfb8aa3b, v42
	v_mul_f32_e32 v47, 0xbfb8aa3b, v43
	v_exp_f32_e32 v46, v46
	v_exp_f32_e32 v47, v47
	v_add_f32_e32 v45, 1.0, v45
	v_rcp_f32_e32 v44, v44
	v_rcp_f32_e32 v45, v45
	v_add_f32_e32 v46, 1.0, v46
	v_add_f32_e32 v47, 1.0, v47
	v_rcp_f32_e32 v46, v46
	v_rcp_f32_e32 v47, v47
	v_pk_mul_f32 v[32:33], v[32:33], v[162:163] op_sel_hi:[1,0]
	v_pk_mul_f32 v[40:41], v[40:41], v[44:45]
	v_pk_mul_f32 v[28:29], v[28:29], v[158:159] op_sel_hi:[1,0]
	v_pk_mul_f32 v[40:41], v[32:33], v[40:41]
	v_pk_mul_f32 v[32:33], v[34:35], v[162:163] op_sel_hi:[1,0]
	v_pk_mul_f32 v[34:35], v[42:43], v[46:47]
	v_pk_mul_f32 v[30:31], v[30:31], v[158:159] op_sel_hi:[1,0]
	v_pk_mul_f32 v[42:43], v[32:33], v[34:35]
	v_cvt_pk_bf16_f32 v32, v36, v37
	v_mad_i64_i32 v[36:37], s[0:1], v150, s59, v[112:113]
	v_cvt_pk_bf16_f32 v33, v38, v39
	v_cvt_pk_bf16_f32 v34, v40, v41
	v_cvt_pk_bf16_f32 v35, v42, v43
	v_lshl_add_u64 v[36:37], v[36:37], 0, v[114:115]
	v_mul_f32_e32 v38, 0xbfb8aa3b, v28
	global_store_dwordx4 v[36:37], v[32:35], off
	v_exp_f32_e32 v38, v38
	v_pk_mul_f32 v[20:21], v[20:21], v[158:159] op_sel_hi:[1,0]
	v_mul_f32_e32 v32, 0xbfb8aa3b, v29
	v_exp_f32_e32 v33, v32
	v_mul_f32_e32 v34, 0xbfb8aa3b, v30
	v_mul_f32_e32 v35, 0xbfb8aa3b, v31
	v_exp_f32_e32 v34, v34
	v_exp_f32_e32 v35, v35
	v_add_f32_e32 v32, 1.0, v38
	v_add_f32_e32 v33, 1.0, v33
	v_rcp_f32_e32 v32, v32
	v_rcp_f32_e32 v33, v33
	v_add_f32_e32 v34, 1.0, v34
	v_add_f32_e32 v35, 1.0, v35
	v_rcp_f32_e32 v34, v34
	v_rcp_f32_e32 v35, v35
	v_pk_mul_f32 v[28:29], v[28:29], v[32:33]
	v_pk_mul_f32 v[24:25], v[24:25], v[158:159] op_sel_hi:[1,0]
	v_pk_mul_f32 v[20:21], v[20:21], v[28:29]
	v_pk_mul_f32 v[28:29], v[30:31], v[34:35]
	v_mul_f32_e32 v30, 0xbfb8aa3b, v24
	v_exp_f32_e32 v30, v30
	v_pk_mul_f32 v[22:23], v[22:23], v[158:159] op_sel_hi:[1,0]
	v_pk_mul_f32 v[26:27], v[26:27], v[158:159] op_sel_hi:[1,0]
	v_pk_mul_f32 v[22:23], v[22:23], v[28:29]
	v_mul_f32_e32 v28, 0xbfb8aa3b, v25
	v_exp_f32_e32 v29, v28
	v_add_f32_e32 v28, 1.0, v30
	v_mul_f32_e32 v30, 0xbfb8aa3b, v26
	v_mul_f32_e32 v31, 0xbfb8aa3b, v27
	v_exp_f32_e32 v30, v30
	v_exp_f32_e32 v31, v31
	v_add_f32_e32 v29, 1.0, v29
	v_rcp_f32_e32 v28, v28
	v_rcp_f32_e32 v29, v29
	v_add_f32_e32 v30, 1.0, v30
	v_add_f32_e32 v31, 1.0, v31
	v_rcp_f32_e32 v30, v30
	v_rcp_f32_e32 v31, v31
	v_pk_mul_f32 v[16:17], v[16:17], v[158:159] op_sel_hi:[1,0]
	v_pk_mul_f32 v[24:25], v[24:25], v[28:29]
	v_pk_mul_f32 v[12:13], v[12:13], v[154:155] op_sel_hi:[1,0]
	v_pk_mul_f32 v[24:25], v[16:17], v[24:25]
	v_pk_mul_f32 v[16:17], v[18:19], v[158:159] op_sel_hi:[1,0]
	v_pk_mul_f32 v[18:19], v[26:27], v[30:31]
	v_pk_mul_f32 v[14:15], v[14:15], v[154:155] op_sel_hi:[1,0]
	v_pk_mul_f32 v[26:27], v[16:17], v[18:19]
	v_cvt_pk_bf16_f32 v16, v20, v21
	v_mad_i64_i32 v[20:21], s[0:1], v148, s59, v[112:113]
	v_cvt_pk_bf16_f32 v17, v22, v23
	v_cvt_pk_bf16_f32 v18, v24, v25
	v_cvt_pk_bf16_f32 v19, v26, v27
	v_lshl_add_u64 v[20:21], v[20:21], 0, v[114:115]
	v_mul_f32_e32 v22, 0xbfb8aa3b, v12
	global_store_dwordx4 v[20:21], v[16:19], off
	v_exp_f32_e32 v22, v22
	v_pk_mul_f32 v[4:5], v[4:5], v[154:155] op_sel_hi:[1,0]
	v_mul_f32_e32 v16, 0xbfb8aa3b, v13
	v_exp_f32_e32 v17, v16
	v_mul_f32_e32 v18, 0xbfb8aa3b, v14
	v_mul_f32_e32 v19, 0xbfb8aa3b, v15
	v_exp_f32_e32 v18, v18
	v_exp_f32_e32 v19, v19
	v_add_f32_e32 v16, 1.0, v22
	v_add_f32_e32 v17, 1.0, v17
	v_rcp_f32_e32 v16, v16
	v_rcp_f32_e32 v17, v17
	v_add_f32_e32 v18, 1.0, v18
	v_add_f32_e32 v19, 1.0, v19
	v_rcp_f32_e32 v18, v18
	v_rcp_f32_e32 v19, v19
	v_pk_mul_f32 v[12:13], v[12:13], v[16:17]
	v_pk_mul_f32 v[8:9], v[8:9], v[154:155] op_sel_hi:[1,0]
	v_pk_mul_f32 v[4:5], v[4:5], v[12:13]
	v_pk_mul_f32 v[12:13], v[14:15], v[18:19]
	v_mul_f32_e32 v14, 0xbfb8aa3b, v8
	v_exp_f32_e32 v14, v14
	v_pk_mul_f32 v[6:7], v[6:7], v[154:155] op_sel_hi:[1,0]
	v_pk_mul_f32 v[10:11], v[10:11], v[154:155] op_sel_hi:[1,0]
	v_pk_mul_f32 v[6:7], v[6:7], v[12:13]
	v_mul_f32_e32 v12, 0xbfb8aa3b, v9
	v_exp_f32_e32 v13, v12
	v_add_f32_e32 v12, 1.0, v14
	v_mul_f32_e32 v14, 0xbfb8aa3b, v10
	v_mul_f32_e32 v15, 0xbfb8aa3b, v11
	v_exp_f32_e32 v14, v14
	v_exp_f32_e32 v15, v15
	v_add_f32_e32 v13, 1.0, v13
	v_rcp_f32_e32 v12, v12
	v_rcp_f32_e32 v13, v13
	v_add_f32_e32 v14, 1.0, v14
	v_add_f32_e32 v15, 1.0, v15
	v_rcp_f32_e32 v14, v14
	v_rcp_f32_e32 v15, v15
	v_pk_mul_f32 v[0:1], v[0:1], v[154:155] op_sel_hi:[1,0]
	v_pk_mul_f32 v[8:9], v[8:9], v[12:13]
	s_and_b64 vcc, exec, s[2:3]
	v_pk_mul_f32 v[8:9], v[0:1], v[8:9]
	v_pk_mul_f32 v[0:1], v[2:3], v[154:155] op_sel_hi:[1,0]
	v_pk_mul_f32 v[2:3], v[10:11], v[14:15]
	s_mov_b32 s5, s12
	v_pk_mul_f32 v[10:11], v[0:1], v[2:3]
	v_cvt_pk_bf16_f32 v0, v4, v5
	v_mad_i64_i32 v[4:5], s[0:1], v146, s59, v[112:113]
	v_cvt_pk_bf16_f32 v1, v6, v7
	v_cvt_pk_bf16_f32 v2, v8, v9
	v_cvt_pk_bf16_f32 v3, v10, v11
	v_lshl_add_u64 v[4:5], v[4:5], 0, v[114:115]
	s_mov_b32 s4, s36
	s_mov_b64 s[42:43], s[40:41]
	s_mov_b64 s[44:45], s[38:39]
	global_store_dwordx4 v[4:5], v[0:3], off
	s_waitcnt vmcnt(8)
	v_xor_b32_e32 v184, 16, v177
	v_xor_b32_e32 v185, 32, v177
	v_lshlrev_b32_e32 v184, 2, v184
	v_lshlrev_b32_e32 v185, 2, v185
	v_mov_b32_e32 v190, s10
	v_pk_add_f32 v[216:217], v[216:217], v[218:219]
	v_pk_add_f32 v[220:221], v[220:221], v[222:223]
	v_pk_add_f32 v[224:225], v[224:225], v[226:227]
	v_pk_add_f32 v[196:197], v[196:197], v[198:199]
	v_pk_add_f32 v[200:201], v[200:201], v[202:203]
	v_pk_add_f32 v[204:205], v[204:205], v[206:207]
	v_pk_add_f32 v[208:209], v[208:209], v[210:211]
	v_pk_add_f32 v[212:213], v[212:213], v[214:215]
	v_add_f32_e32 v216, v216, v217
	v_add_f32_e32 v220, v220, v221
	v_add_f32_e32 v224, v224, v225
	v_add_f32_e32 v196, v196, v197
	v_add_f32_e32 v200, v200, v201
	v_add_f32_e32 v204, v204, v205
	v_add_f32_e32 v208, v208, v209
	v_add_f32_e32 v212, v212, v213
	ds_bpermute_b32 v218, v184, v216
	ds_bpermute_b32 v219, v184, v220
	ds_bpermute_b32 v222, v184, v224
	ds_bpermute_b32 v223, v184, v196
	ds_bpermute_b32 v226, v184, v200
	ds_bpermute_b32 v227, v184, v204
	ds_bpermute_b32 v198, v184, v208
	ds_bpermute_b32 v199, v184, v212
	s_waitcnt lgkmcnt(0)
	v_add_f32_e32 v216, v216, v218
	v_add_f32_e32 v220, v220, v219
	v_add_f32_e32 v224, v224, v222
	v_add_f32_e32 v196, v196, v223
	v_add_f32_e32 v200, v200, v226
	v_add_f32_e32 v204, v204, v227
	v_add_f32_e32 v208, v208, v198
	v_add_f32_e32 v212, v212, v199
	ds_bpermute_b32 v218, v185, v216
	ds_bpermute_b32 v219, v185, v220
	ds_bpermute_b32 v222, v185, v224
	ds_bpermute_b32 v223, v185, v196
	ds_bpermute_b32 v226, v185, v200
	ds_bpermute_b32 v227, v185, v204
	ds_bpermute_b32 v198, v185, v208
	ds_bpermute_b32 v199, v185, v212
	s_waitcnt lgkmcnt(0)
	v_add_f32_e32 v216, v216, v218
	v_add_f32_e32 v220, v220, v219
	v_add_f32_e32 v224, v224, v222
	v_add_f32_e32 v196, v196, v223
	v_add_f32_e32 v200, v200, v226
	v_add_f32_e32 v204, v204, v227
	v_add_f32_e32 v208, v208, v198
	v_add_f32_e32 v212, v212, v199
	v_fma_f32 v216, v216, s8, v190
	v_fma_f32 v220, v220, s8, v190
	v_fma_f32 v224, v224, s8, v190
	v_fma_f32 v196, v196, s8, v190
	v_fma_f32 v200, v200, s8, v190
	v_fma_f32 v204, v204, s8, v190
	v_fma_f32 v208, v208, s8, v190
	v_fma_f32 v212, v212, s8, v190
	v_rsq_f32_e32 v240, v216
	v_rsq_f32_e32 v176, v220
	v_rsq_f32_e32 v174, v224
	v_rsq_f32_e32 v170, v196
	v_rsq_f32_e32 v166, v200
	v_rsq_f32_e32 v162, v204
	v_rsq_f32_e32 v158, v208
	v_rsq_f32_e32 v241, v212
	s_and_b64 vcc, exec, s[2:3]
	s_mov_b32 s5, s12
	s_mov_b32 s4, s36
	s_cbranch_vccz .LBB0_1090
	s_waitcnt vmcnt(0)
	s_cmpk_gt_u32 s9, 0xff
	s_cbranch_scc1 .LBB0_1097
	s_barrier
